# one static priority raise for the tid>=256 half-workgroup per GEMM phase (proj/merge/out) instead of per-MFMA-block s_setprio toggles
# speedup vs baseline: 1.0280x; 1.0032x over previous
.Ltr_p_reenter:
	v_readfirstlane_b32 s0, v153
	s_cmpk_gt_u32 s0, 0xff
	s_cbranch_scc0 .Lprio_p
	s_setprio 1

; #define PG8_STAGE(bufoff, gbase, voff) do { _Pragma("unroll") for (int _i = 0; _i < 2; ++_i) \
;         __builtin_amdgcn_global_load_lds((const unsigned*)((const char*)(gbase) + (voff)[_i]), (PG8_LAS unsigned*)(lds + (bufoff) + ldsw + _i * 8192), 16, 0, 0); } while (0)
; #define PG8_LDA(dst, b, h) do { _Pragma("unroll") for (int m = 0; m < 4; ++m) _Pragma("unroll") for (int k = 0; k < 2; ++k) dst[m][k] = *(const PG8_LAS bf16x8*)(lds + PG8_SA(b, h) + aoff + m * 2048 + k * 1024); } while (0)
; #define PG8_LDB(dst, b, h) do { _Pragma("unroll") for (int n = 0; n < 2; ++n) _Pragma("unroll") for (int k = 0; k < 2; ++k) dst[n][k] = *(const PG8_LAS bf16x8*)(lds + PG8_SB(b, h) + boff + n * 2048 + k * 1024); } while (0)
; #define PG8_MMA(ai, bj, At, Bt) do { __builtin_amdgcn_s_setprio(1); _Pragma("unroll") for (int m = 0; m < 4; ++m) _Pragma("unroll") for (int n = 0; n < 2; ++n) _Pragma("unroll") for (int k = 0; k < 2; ++k) \
;         acc[ai][bj][m][n] = __builtin_amdgcn_mfma_f32_16x16x32_bf16(Bt[n][k], At[m][k], acc[ai][bj][m][n], 0, 0, 0); __builtin_amdgcn_s_setprio(0); } while (0)
; template <class Epi, class Sched>
; __device__ __forceinline__ void gemm_phase(PG8_LAS unsigned char* lds, const Gemm g, const Sched& S, const Epi& E) {
;     ...
;             PG8_LDB(B0, 0, 0); PG8_SCHED; PG8_LDA(At, 0, 0); PG8_STAGE(PG8_SA(1, 1), a1 + hstep, voffA);
;             PG8_WAIT_L(8); PG8_BAR; PG8_WAIT_L(0); PG8_MMA(0, 0, At, B0); PG8_BAR; PG8_SCHED;
;             PG8_LDB(B1, 0, 1); PG8_STAGE(PG8_SB(0, 0), b2, voffB);
;             PG8_BAR; PG8_WAIT_L(0); PG8_MMA(0, 1, At, B1); PG8_BAR;
;             PG8_LDA(At, 0, 1); PG8_STAGE(PG8_SA(0, 0), a2, voffA);
;             PG8_BAR; PG8_WAIT_L(0); PG8_MMA(1, 0, At, B0); PG8_BAR; PG8_SCHED;
;             PG8_STAGE(PG8_SB(0, 1), b2 + hstep, voffB);
;             PG8_WAIT_V(6); PG8_BAR; PG8_MMA(1, 1, At, B1); PG8_BAR;
;             PG8_LDB(B0, 1, 0); PG8_SCHED; PG8_LDA(At, 1, 0); PG8_STAGE(PG8_SA(0, 1), a2 + hstep, voffA);
;             PG8_WAIT_L(8); PG8_BAR; PG8_WAIT_L(0); PG8_MMA(0, 0, At, B0); PG8_BAR; PG8_SCHED;
;             PG8_LDB(B1, 1, 1); PG8_STAGE(PG8_SB(1, 0), b3, voffB);
;             PG8_BAR; PG8_WAIT_L(0); PG8_MMA(0, 1, At, B1); PG8_BAR;
;             PG8_LDA(At, 1, 1); PG8_STAGE(PG8_SA(1, 0), a3, voffA);
;             PG8_BAR; PG8_WAIT_L(0); PG8_MMA(1, 0, At, B0); PG8_BAR; PG8_SCHED;
.LBB0_130:
	s_add_u32 s4, s2, 0xfffc0080
	s_addc_u32 s5, s3, -1
	s_add_i32 s28, 0, 0x10000
	v_add_u32_e32 v16, s28, v178
	ds_read_b128 v[134:137], v16
	ds_read_b128 v[162:165], v16 offset:1024
	ds_read_b128 v[166:169], v16 offset:2048
	ds_read_b128 v[170:173], v16 offset:3072
	s_cmp_eq_u32 s27, 12
	s_cselect_b32 s7, s11, s5
	s_cselect_b32 s6, s22, s4
	s_cselect_b32 s5, s9, s26
	s_cselect_b32 s4, s24, s25
	v_lshl_add_u64 v[150:151], s[2:3], 0, v[146:147]
	s_add_i32 m0, s38, 0xc000
	ds_read_b128 v[174:177], v194
	ds_read_b128 v[196:199], v194 offset:1024
	ds_read_b128 v[200:203], v194 offset:2048
	ds_read_b128 v[204:207], v194 offset:3072
	ds_read_b128 v[208:211], v194 offset:4096
	ds_read_b128 v[212:215], v194 offset:5120
	ds_read_b128 v[216:219], v194 offset:6144
	ds_read_b128 v[220:223], v194 offset:7168
	global_load_lds_dwordx4 v[150:151], off
	v_lshl_add_u64 v[150:151], s[2:3], 0, v[148:149]
	s_add_i32 m0, s38, 0xe000
	s_nop 0
	global_load_lds_dwordx4 v[150:151], off
	s_waitcnt lgkmcnt(8)
	s_barrier
	s_waitcnt lgkmcnt(0)
	s_waitcnt lgkmcnt(0)
	v_mfma_f32_16x16x32_bf16 v[130:133], v[134:137], v[174:177], v[130:133]
	v_mfma_f32_16x16x32_bf16 v[126:129], v[166:169], v[174:177], v[126:129]
	v_mfma_f32_16x16x32_bf16 v[122:125], v[134:137], v[200:203], v[122:125]
	v_mfma_f32_16x16x32_bf16 v[118:121], v[166:169], v[200:203], v[118:121]
	v_mfma_f32_16x16x32_bf16 v[114:117], v[134:137], v[208:211], v[114:117]
	v_mfma_f32_16x16x32_bf16 v[110:113], v[166:169], v[208:211], v[110:113]
	v_mfma_f32_16x16x32_bf16 v[106:109], v[134:137], v[216:219], v[106:109]
	v_mfma_f32_16x16x32_bf16 v[102:105], v[166:169], v[216:219], v[102:105]
	v_mfma_f32_16x16x32_bf16 v[130:133], v[162:165], v[196:199], v[130:133]
	v_mfma_f32_16x16x32_bf16 v[126:129], v[170:173], v[196:199], v[126:129]
	v_mfma_f32_16x16x32_bf16 v[122:125], v[162:165], v[204:207], v[122:125]
	v_mfma_f32_16x16x32_bf16 v[118:121], v[170:173], v[204:207], v[118:121]
	v_mfma_f32_16x16x32_bf16 v[114:117], v[162:165], v[212:215], v[114:117]
	v_mfma_f32_16x16x32_bf16 v[110:113], v[170:173], v[212:215], v[110:113]
	v_mfma_f32_16x16x32_bf16 v[106:109], v[162:165], v[220:223], v[106:109]
	v_mfma_f32_16x16x32_bf16 v[102:105], v[170:173], v[220:223], v[102:105]
	s_barrier
	s_add_i32 s30, 0, 0x14000
	s_add_i32 s28, s28, s37
	v_add_u32_e32 v16, s30, v178
	v_lshl_add_u64 v[150:151], s[4:5], 0, v[138:139]
	s_mov_b32 m0, s28
	ds_read_b128 v[224:227], v16
	ds_read_b128 v[228:231], v16 offset:1024
	ds_read_b128 v[232:235], v16 offset:2048
	ds_read_b128 v[236:239], v16 offset:3072
	global_load_lds_dwordx4 v[150:151], off
	v_lshl_add_u64 v[240:241], s[4:5], 0, v[142:143]
	s_add_i32 m0, s28, 0x2000
	s_nop 0
	global_load_lds_dwordx4 v[240:241], off
	s_barrier
	s_waitcnt lgkmcnt(0)
	s_waitcnt lgkmcnt(0)
	v_mfma_f32_16x16x32_bf16 v[66:69], v[224:227], v[174:177], v[66:69]
	v_mfma_f32_16x16x32_bf16 v[62:65], v[232:235], v[174:177], v[62:65]
	v_mfma_f32_16x16x32_bf16 v[58:61], v[224:227], v[200:203], v[58:61]
	v_mfma_f32_16x16x32_bf16 v[54:57], v[232:235], v[200:203], v[54:57]
	v_mfma_f32_16x16x32_bf16 v[50:53], v[224:227], v[208:211], v[50:53]
	v_mfma_f32_16x16x32_bf16 v[46:49], v[232:235], v[208:211], v[46:49]
	v_mfma_f32_16x16x32_bf16 v[42:45], v[224:227], v[216:219], v[42:45]
	v_mfma_f32_16x16x32_bf16 v[38:41], v[232:235], v[216:219], v[38:41]
	v_mfma_f32_16x16x32_bf16 v[66:69], v[228:231], v[196:199], v[66:69]
	v_mfma_f32_16x16x32_bf16 v[62:65], v[236:239], v[196:199], v[62:65]
	v_mfma_f32_16x16x32_bf16 v[58:61], v[228:231], v[204:207], v[58:61]
	v_mfma_f32_16x16x32_bf16 v[54:57], v[236:239], v[204:207], v[54:57]
	v_mfma_f32_16x16x32_bf16 v[50:53], v[228:231], v[212:215], v[50:53]
	v_mfma_f32_16x16x32_bf16 v[46:49], v[236:239], v[212:215], v[46:49]
	v_mfma_f32_16x16x32_bf16 v[42:45], v[228:231], v[220:223], v[42:45]
	v_mfma_f32_16x16x32_bf16 v[38:41], v[236:239], v[220:223], v[38:41]
	s_mov_b32 m0, s38
	v_lshl_add_u64 v[242:243], s[6:7], 0, v[18:19]
	s_barrier
	ds_read_b128 v[174:177], v194 offset:16384
	ds_read_b128 v[196:199], v194 offset:17408
	ds_read_b128 v[200:203], v194 offset:18432
	ds_read_b128 v[204:207], v194 offset:19456
	ds_read_b128 v[208:211], v194 offset:20480
	ds_read_b128 v[212:215], v194 offset:21504
	ds_read_b128 v[216:219], v194 offset:22528
	ds_read_b128 v[220:223], v194 offset:23552
	global_load_lds_dwordx4 v[242:243], off
	v_lshl_add_u64 v[244:245], s[6:7], 0, v[140:141]
	s_mov_b32 m0, s39
	s_nop 0
	global_load_lds_dwordx4 v[244:245], off
	s_barrier
	s_waitcnt lgkmcnt(0)
	s_waitcnt lgkmcnt(0)
	v_mfma_f32_16x16x32_bf16 v[98:101], v[134:137], v[174:177], v[98:101]
	v_mfma_f32_16x16x32_bf16 v[94:97], v[166:169], v[174:177], v[94:97]
	v_mfma_f32_16x16x32_bf16 v[90:93], v[134:137], v[200:203], v[90:93]
	v_mfma_f32_16x16x32_bf16 v[86:89], v[166:169], v[200:203], v[86:89]
	v_mfma_f32_16x16x32_bf16 v[82:85], v[134:137], v[208:211], v[82:85]
	v_mfma_f32_16x16x32_bf16 v[78:81], v[166:169], v[208:211], v[78:81]
	v_mfma_f32_16x16x32_bf16 v[74:77], v[134:137], v[216:219], v[74:77]
	v_mfma_f32_16x16x32_bf16 v[70:73], v[166:169], v[216:219], v[70:73]
	v_mfma_f32_16x16x32_bf16 v[98:101], v[162:165], v[196:199], v[98:101]
	v_mfma_f32_16x16x32_bf16 v[94:97], v[170:173], v[196:199], v[94:97]
	v_mfma_f32_16x16x32_bf16 v[90:93], v[162:165], v[204:207], v[90:93]
	v_mfma_f32_16x16x32_bf16 v[86:89], v[170:173], v[204:207], v[86:89]
	v_mfma_f32_16x16x32_bf16 v[82:85], v[162:165], v[212:215], v[82:85]
	v_mfma_f32_16x16x32_bf16 v[78:81], v[170:173], v[212:215], v[78:81]
	v_mfma_f32_16x16x32_bf16 v[74:77], v[162:165], v[220:223], v[74:77]
	v_mfma_f32_16x16x32_bf16 v[70:73], v[170:173], v[220:223], v[70:73]
	s_barrier
; #define PG8_STAGE(bufoff, gbase, voff) do { _Pragma("unroll") for (int _i = 0; _i < 2; ++_i) \
;         __builtin_amdgcn_global_load_lds((const unsigned*)((const char*)(gbase) + (voff)[_i]), (PG8_LAS unsigned*)(lds + (bufoff) + ldsw + _i * 8192), 16, 0, 0); } while (0)
; #define PG8_LDA(dst, b, h) do { _Pragma("unroll") for (int m = 0; m < 4; ++m) _Pragma("unroll") for (int k = 0; k < 2; ++k) dst[m][k] = *(const PG8_LAS bf16x8*)(lds + PG8_SA(b, h) + aoff + m * 2048 + k * 1024); } while (0)
; #define PG8_LDB(dst, b, h) do { _Pragma("unroll") for (int n = 0; n < 2; ++n) _Pragma("unroll") for (int k = 0; k < 2; ++k) dst[n][k] = *(const PG8_LAS bf16x8*)(lds + PG8_SB(b, h) + boff + n * 2048 + k * 1024); } while (0)
; #define PG8_MMA(ai, bj, At, Bt) do { __builtin_amdgcn_s_setprio(1); _Pragma("unroll") for (int m = 0; m < 4; ++m) _Pragma("unroll") for (int n = 0; n < 2; ++n) _Pragma("unroll") for (int k = 0; k < 2; ++k) \
;         acc[ai][bj][m][n] = __builtin_amdgcn_mfma_f32_16x16x32_bf16(Bt[n][k], At[m][k], acc[ai][bj][m][n], 0, 0, 0); __builtin_amdgcn_s_setprio(0); } while (0)
; #define PG8_WAIT_V(n) asm volatile("s_waitcnt vmcnt(" #n ")" ::: "memory")
; #define PG8_WAIT_L(n) asm volatile("s_waitcnt lgkmcnt(" #n ")" ::: "memory")
; #define PG8_BAR __builtin_amdgcn_s_barrier()
; #define PG8_SCHED __builtin_amdgcn_sched_barrier(0)
; template <class Epi, class Sched>
; __device__ __forceinline__ void gemm_phase(PG8_LAS unsigned char* lds, const Gemm g, const Sched& S, const Epi& E) {
;     ...
;             PG8_BAR; PG8_WAIT_L(0); PG8_MMA(1, 0, At, B0); PG8_BAR; PG8_SCHED;
;             PG8_STAGE(PG8_SB(0, 1), b2 + hstep, voffB);
;             PG8_WAIT_V(6); PG8_BAR; PG8_MMA(1, 1, At, B1); PG8_BAR;
;             PG8_LDB(B0, 1, 0); PG8_SCHED; PG8_LDA(At, 1, 0); PG8_STAGE(PG8_SA(0, 1), a2 + hstep, voffA);
;             PG8_WAIT_L(8); PG8_BAR; PG8_WAIT_L(0); PG8_MMA(0, 0, At, B0); PG8_BAR; PG8_SCHED;
;             PG8_LDB(B1, 1, 1); PG8_STAGE(PG8_SB(1, 0), b3, voffB);
;             PG8_BAR; PG8_WAIT_L(0); PG8_MMA(0, 1, At, B1); PG8_BAR;
;             PG8_LDA(At, 1, 1); PG8_STAGE(PG8_SA(1, 0), a3, voffA);
;             PG8_BAR; PG8_WAIT_L(0); PG8_MMA(1, 0, At, B0); PG8_BAR; PG8_SCHED;
	s_add_u32 s28, s4, 0x40000
	s_addc_u32 s29, s5, 0
	s_add_i32 s30, s30, s37
	v_lshl_add_u64 v[134:135], s[28:29], 0, v[138:139]
	s_mov_b32 m0, s30
	s_nop 0
	global_load_lds_dwordx4 v[134:135], off
	v_lshl_add_u64 v[134:135], s[28:29], 0, v[142:143]
	s_add_i32 m0, s30, 0x2000
	s_nop 0
	global_load_lds_dwordx4 v[134:135], off
	s_waitcnt vmcnt(6)
	s_barrier
	v_mfma_f32_16x16x32_bf16 v[34:37], v[224:227], v[174:177], v[34:37]
	v_mfma_f32_16x16x32_bf16 v[30:33], v[232:235], v[174:177], v[30:33]
	v_mfma_f32_16x16x32_bf16 v[26:29], v[224:227], v[200:203], v[26:29]
	v_mfma_f32_16x16x32_bf16 v[22:25], v[232:235], v[200:203], v[22:25]
	v_mfma_f32_16x16x32_bf16 v[12:15], v[224:227], v[208:211], v[12:15]
	v_mfma_f32_16x16x32_bf16 v[8:11], v[232:235], v[208:211], v[8:11]
	v_mfma_f32_16x16x32_bf16 v[4:7], v[224:227], v[216:219], v[4:7]
	v_mfma_f32_16x16x32_bf16 v[0:3], v[232:235], v[216:219], v[0:3]
	v_mfma_f32_16x16x32_bf16 v[34:37], v[228:231], v[196:199], v[34:37]
	v_mfma_f32_16x16x32_bf16 v[30:33], v[236:239], v[196:199], v[30:33]
	v_mfma_f32_16x16x32_bf16 v[26:29], v[228:231], v[204:207], v[26:29]
	v_mfma_f32_16x16x32_bf16 v[22:25], v[236:239], v[204:207], v[22:25]
	v_mfma_f32_16x16x32_bf16 v[12:15], v[228:231], v[212:215], v[12:15]
	v_mfma_f32_16x16x32_bf16 v[8:11], v[236:239], v[212:215], v[8:11]
	v_mfma_f32_16x16x32_bf16 v[4:7], v[228:231], v[220:223], v[4:7]
	v_mfma_f32_16x16x32_bf16 v[0:3], v[236:239], v[220:223], v[0:3]
	s_add_i32 s28, 0, 0x18000
	v_add_u32_e32 v16, s28, v178
	s_barrier
	ds_read_b128 v[134:137], v16
	ds_read_b128 v[162:165], v16 offset:1024
	ds_read_b128 v[166:169], v16 offset:2048
	ds_read_b128 v[170:173], v16 offset:3072
	s_add_u32 s6, s6, 0x40000
	s_addc_u32 s7, s7, 0
	s_mov_b32 m0, s40
	v_lshl_add_u64 v[224:225], s[6:7], 0, v[18:19]
	ds_read_b128 v[174:177], v194 offset:32768
	ds_read_b128 v[196:199], v194 offset:33792
	ds_read_b128 v[200:203], v194 offset:34816
	ds_read_b128 v[204:207], v194 offset:35840
	ds_read_b128 v[208:211], v194 offset:36864
	ds_read_b128 v[212:215], v194 offset:37888
	ds_read_b128 v[216:219], v194 offset:38912
	ds_read_b128 v[220:223], v194 offset:39936
	global_load_lds_dwordx4 v[224:225], off
	v_lshl_add_u64 v[224:225], s[6:7], 0, v[140:141]
	s_mov_b32 m0, s41
	s_nop 0
	global_load_lds_dwordx4 v[224:225], off
	s_waitcnt lgkmcnt(8)
	s_barrier
	s_waitcnt lgkmcnt(0)
	s_waitcnt lgkmcnt(0)
	v_mfma_f32_16x16x32_bf16 v[130:133], v[134:137], v[174:177], v[130:133]
	v_mfma_f32_16x16x32_bf16 v[126:129], v[166:169], v[174:177], v[126:129]
	v_mfma_f32_16x16x32_bf16 v[122:125], v[134:137], v[200:203], v[122:125]
	v_mfma_f32_16x16x32_bf16 v[118:121], v[166:169], v[200:203], v[118:121]
	v_mfma_f32_16x16x32_bf16 v[114:117], v[134:137], v[208:211], v[114:117]
	v_mfma_f32_16x16x32_bf16 v[110:113], v[166:169], v[208:211], v[110:113]
	v_mfma_f32_16x16x32_bf16 v[106:109], v[134:137], v[216:219], v[106:109]
	v_mfma_f32_16x16x32_bf16 v[102:105], v[166:169], v[216:219], v[102:105]
	v_mfma_f32_16x16x32_bf16 v[130:133], v[162:165], v[196:199], v[130:133]
	v_mfma_f32_16x16x32_bf16 v[126:129], v[170:173], v[196:199], v[126:129]
	v_mfma_f32_16x16x32_bf16 v[122:125], v[162:165], v[204:207], v[122:125]
	v_mfma_f32_16x16x32_bf16 v[118:121], v[170:173], v[204:207], v[118:121]
	v_mfma_f32_16x16x32_bf16 v[114:117], v[162:165], v[212:215], v[114:117]
	v_mfma_f32_16x16x32_bf16 v[110:113], v[170:173], v[212:215], v[110:113]
	v_mfma_f32_16x16x32_bf16 v[106:109], v[162:165], v[220:223], v[106:109]
	v_mfma_f32_16x16x32_bf16 v[102:105], v[170:173], v[220:223], v[102:105]
	s_barrier
	s_add_i32 s6, 0, 0x1c000
	s_add_i32 s7, s28, s37
	v_add_u32_e32 v16, s6, v178
	v_lshl_add_u64 v[150:151], v[150:151], 0, s[50:51]
	s_mov_b32 m0, s7
	ds_read_b128 v[224:227], v16
	ds_read_b128 v[228:231], v16 offset:1024
	ds_read_b128 v[232:235], v16 offset:2048
	ds_read_b128 v[236:239], v16 offset:3072
	global_load_lds_dwordx4 v[150:151], off
	v_lshl_add_u64 v[150:151], v[240:241], 0, s[50:51]
	s_add_i32 m0, s7, 0x2000
	s_nop 0
	global_load_lds_dwordx4 v[150:151], off
	s_barrier
; #define PG8_WAIT_V(n) asm volatile("s_waitcnt vmcnt(" #n ")" ::: "memory")
; template <class Epi, class Sched>
; __device__ __forceinline__ void gemm_phase(PG8_LAS unsigned char* lds, const Gemm g, const Sched& S, const Epi& E) {
;     ...
;             PG8_LDB(B0, 0, 0); PG8_SCHED; PG8_LDA(At, 0, 0); PG8_STAGE(PG8_SA(1, 1), a1 + hstep, voffA);
;             PG8_WAIT_L(8); PG8_BAR; PG8_WAIT_L(0); PG8_MMA(0, 0, At, B0); PG8_BAR; PG8_SCHED;
;             PG8_LDB(B1, 0, 1); PG8_STAGE(PG8_SB(0, 0), b2, voffB);
;             PG8_BAR; PG8_WAIT_L(0); PG8_MMA(0, 1, At, B1); PG8_BAR;
;             PG8_LDA(At, 0, 1); PG8_STAGE(PG8_SA(0, 0), a2, voffA);
;             PG8_BAR; PG8_WAIT_L(0); PG8_MMA(1, 0, At, B0); PG8_BAR; PG8_SCHED;
;             PG8_STAGE(PG8_SB(0, 1), b2 + hstep, voffB);
;             PG8_WAIT_V(6); PG8_BAR; PG8_MMA(1, 1, At, B1); PG8_BAR;
;             PG8_LDB(B0, 1, 0); PG8_SCHED; PG8_LDA(At, 1, 0); PG8_STAGE(PG8_SA(0, 1), a2 + hstep, voffA);
;             PG8_WAIT_L(8); PG8_BAR; PG8_WAIT_L(0); PG8_MMA(0, 0, At, B0); PG8_BAR; PG8_SCHED;
;             PG8_LDB(B1, 1, 1); PG8_STAGE(PG8_SB(1, 0), b3, voffB);
;             PG8_BAR; PG8_WAIT_L(0); PG8_MMA(0, 1, At, B1); PG8_BAR;
;             PG8_LDA(At, 1, 1); PG8_STAGE(PG8_SA(1, 0), a3, voffA);
;             PG8_BAR; PG8_WAIT_L(0); PG8_MMA(1, 0, At, B0); PG8_BAR; PG8_SCHED;
;             PG8_STAGE(PG8_SB(1, 1), b3 + hstep, voffB);
;             PG8_WAIT_V(6); PG8_BAR; PG8_MMA(1, 1, At, B1); PG8_BAR;
;   template <int GRP>
;   DI void run(const f32x4 (&acc)[2][2][4][2], const pg8::Unit& u, int wr, int wc, int fr, int fq) const {
;     ...
;       const bool simple = (nt < 4) || (nt >= 12 && nt < 20) || (nt >= 21 && nt < 29) || (nt >= 30);
;       if (simple) {
;         size_t off; int ld, c0, act;
;         if (nt < 4) { off = OFF_QAB; ld = 1024; c0 = nt * 128; act = 0; }
;         else if (nt < 16) { off = OFF_GA; ld = 512; c0 = (nt - 12) * 128; act = 1; }
;         else if (nt < 20) { off = OFF_QAB; ld = 1024; c0 = 512 + (nt - 16) * 128; act = 0; }
;         else if (nt < 25) { off = OFF_GB; ld = 512; c0 = (nt - 21) * 128; act = 1; }
;         else if (nt < 29) { off = OFF_QI; ld = 512; c0 = (nt - 25) * 128; act = 0; }
;         else if (nt < 38) { off = OFF_RA; ld = 1024; c0 = (nt - 30) * 128; act = 2; }
;         else { off = OFF_RB; ld = 1024; c0 = (nt - 38) * 128; act = 2; }
	s_waitcnt lgkmcnt(0)
	s_waitcnt lgkmcnt(0)
	v_mfma_f32_16x16x32_bf16 v[66:69], v[224:227], v[174:177], v[66:69]
	v_mfma_f32_16x16x32_bf16 v[62:65], v[232:235], v[174:177], v[62:65]
	v_mfma_f32_16x16x32_bf16 v[58:61], v[224:227], v[200:203], v[58:61]
	v_mfma_f32_16x16x32_bf16 v[54:57], v[232:235], v[200:203], v[54:57]
	v_mfma_f32_16x16x32_bf16 v[50:53], v[224:227], v[208:211], v[50:53]
	v_mfma_f32_16x16x32_bf16 v[46:49], v[232:235], v[208:211], v[46:49]
	v_mfma_f32_16x16x32_bf16 v[42:45], v[224:227], v[216:219], v[42:45]
	v_mfma_f32_16x16x32_bf16 v[38:41], v[232:235], v[216:219], v[38:41]
	v_mfma_f32_16x16x32_bf16 v[66:69], v[228:231], v[196:199], v[66:69]
	v_mfma_f32_16x16x32_bf16 v[62:65], v[236:239], v[196:199], v[62:65]
	v_mfma_f32_16x16x32_bf16 v[58:61], v[228:231], v[204:207], v[58:61]
	v_mfma_f32_16x16x32_bf16 v[54:57], v[236:239], v[204:207], v[54:57]
	v_mfma_f32_16x16x32_bf16 v[50:53], v[228:231], v[212:215], v[50:53]
	v_mfma_f32_16x16x32_bf16 v[46:49], v[236:239], v[212:215], v[46:49]
	v_mfma_f32_16x16x32_bf16 v[42:45], v[228:231], v[220:223], v[42:45]
	v_mfma_f32_16x16x32_bf16 v[38:41], v[236:239], v[220:223], v[38:41]
	s_mov_b32 m0, s43
	v_lshl_add_u64 v[150:151], v[242:243], 0, s[50:51]
	s_barrier
	ds_read_b128 v[174:177], v194 offset:49152
	ds_read_b128 v[196:199], v194 offset:50176
	ds_read_b128 v[200:203], v194 offset:51200
	ds_read_b128 v[204:207], v194 offset:52224
	ds_read_b128 v[208:211], v194 offset:53248
	ds_read_b128 v[212:215], v194 offset:54272
	ds_read_b128 v[216:219], v194 offset:55296
	ds_read_b128 v[220:223], v194 offset:56320
	global_load_lds_dwordx4 v[150:151], off
	v_lshl_add_u64 v[150:151], v[244:245], 0, s[50:51]
	s_mov_b32 m0, s44
	s_nop 0
	global_load_lds_dwordx4 v[150:151], off
	s_barrier
	s_waitcnt lgkmcnt(0)
	s_waitcnt lgkmcnt(0)
	v_mfma_f32_16x16x32_bf16 v[98:101], v[134:137], v[174:177], v[98:101]
	v_mfma_f32_16x16x32_bf16 v[94:97], v[166:169], v[174:177], v[94:97]
	v_mfma_f32_16x16x32_bf16 v[90:93], v[134:137], v[200:203], v[90:93]
	v_mfma_f32_16x16x32_bf16 v[86:89], v[166:169], v[200:203], v[86:89]
	v_mfma_f32_16x16x32_bf16 v[82:85], v[134:137], v[208:211], v[82:85]
	v_mfma_f32_16x16x32_bf16 v[78:81], v[166:169], v[208:211], v[78:81]
	v_mfma_f32_16x16x32_bf16 v[74:77], v[134:137], v[216:219], v[74:77]
	v_mfma_f32_16x16x32_bf16 v[70:73], v[166:169], v[216:219], v[70:73]
	v_mfma_f32_16x16x32_bf16 v[98:101], v[162:165], v[196:199], v[98:101]
	v_mfma_f32_16x16x32_bf16 v[94:97], v[170:173], v[196:199], v[94:97]
	v_mfma_f32_16x16x32_bf16 v[90:93], v[162:165], v[204:207], v[90:93]
	v_mfma_f32_16x16x32_bf16 v[86:89], v[170:173], v[204:207], v[86:89]
	v_mfma_f32_16x16x32_bf16 v[82:85], v[162:165], v[212:215], v[82:85]
	v_mfma_f32_16x16x32_bf16 v[78:81], v[170:173], v[212:215], v[78:81]
	v_mfma_f32_16x16x32_bf16 v[74:77], v[162:165], v[220:223], v[74:77]
	v_mfma_f32_16x16x32_bf16 v[70:73], v[170:173], v[220:223], v[70:73]
	s_barrier
	s_add_u32 s4, s4, 0x40080
	s_addc_u32 s5, s5, 0
	s_add_i32 s6, s6, s37
	v_lshl_add_u64 v[134:135], s[4:5], 0, v[138:139]
	s_mov_b32 m0, s6
	s_nop 0
	global_load_lds_dwordx4 v[134:135], off
	v_lshl_add_u64 v[134:135], s[4:5], 0, v[142:143]
	s_add_i32 m0, s6, 0x2000
	s_nop 0
	global_load_lds_dwordx4 v[134:135], off
	s_waitcnt vmcnt(6)
	s_barrier
	v_mfma_f32_16x16x32_bf16 v[34:37], v[224:227], v[174:177], v[34:37]
	v_mfma_f32_16x16x32_bf16 v[30:33], v[232:235], v[174:177], v[30:33]
	v_mfma_f32_16x16x32_bf16 v[26:29], v[224:227], v[200:203], v[26:29]
	v_mfma_f32_16x16x32_bf16 v[22:25], v[232:235], v[200:203], v[22:25]
	v_mfma_f32_16x16x32_bf16 v[12:15], v[224:227], v[208:211], v[12:15]
	v_mfma_f32_16x16x32_bf16 v[8:11], v[232:235], v[208:211], v[8:11]
	v_mfma_f32_16x16x32_bf16 v[4:7], v[224:227], v[216:219], v[4:7]
	v_mfma_f32_16x16x32_bf16 v[0:3], v[232:235], v[216:219], v[0:3]
	v_mfma_f32_16x16x32_bf16 v[34:37], v[228:231], v[196:199], v[34:37]
	v_mfma_f32_16x16x32_bf16 v[30:33], v[236:239], v[196:199], v[30:33]
	v_mfma_f32_16x16x32_bf16 v[26:29], v[228:231], v[204:207], v[26:29]
	v_mfma_f32_16x16x32_bf16 v[22:25], v[236:239], v[204:207], v[22:25]
	v_mfma_f32_16x16x32_bf16 v[12:15], v[228:231], v[212:215], v[12:15]
	v_mfma_f32_16x16x32_bf16 v[8:11], v[236:239], v[212:215], v[8:11]
	v_mfma_f32_16x16x32_bf16 v[4:7], v[228:231], v[220:223], v[4:7]
	v_mfma_f32_16x16x32_bf16 v[0:3], v[236:239], v[220:223], v[0:3]
	s_add_i32 s27, s27, 2
	s_add_u32 s2, s2, 0x100
	s_addc_u32 s3, s3, 0
	s_add_u32 s25, s25, 0x100
	s_addc_u32 s26, s26, 0
	s_cmp_gt_u32 s27, 13
	s_barrier
	s_cbranch_scc0 .LBB0_130
	s_lshl_b32 s9, s23, 1
	s_lshl_b32 s22, s23, 8
	s_cmp_gt_i32 s9, 3
	s_cselect_b64 s[2:3], -1, 0
	v_cndmask_b32_e64 v16, 0, 1, s[2:3]
	s_cmpk_gt_i32 s48, 0xff
	v_lshl_add_u32 v195, s23, 10, v193
	s_mov_b64 s[4:5], -1
	v_cmp_ne_u32_e64 s[2:3], 1, v16
	s_cbranch_scc0 .LBB0_923
	s_and_b64 vcc, exec, s[2:3]
	s_cbranch_vccnz .LBB0_137
	s_cmp_lt_i32 s9, 22
	s_cbranch_scc1 .LBB0_138
	s_cmp_gt_i32 s9, 25
	s_cbranch_scc0 .LBB0_139
	s_cmp_gt_i32 s9, 27
	s_cbranch_scc0 .LBB0_140
	s_cmp_lg_u32 s9, 28
	s_mov_b64 s[24:25], -1
	s_cselect_b64 s[4:5], -1, 0
	s_cbranch_execz .LBB0_141
	s_branch .LBB0_142

; DI int otid() { int t = threadIdx.x; asm volatile("" : "+v"(t)); return t; }
; #define PG8_WAIT_V(n) asm volatile("s_waitcnt vmcnt(" #n ")" ::: "memory")
; #define PG8_BAR __builtin_amdgcn_s_barrier()
; DI void gbar(unsigned* ctr, unsigned target) {
;   asm volatile("s_waitcnt vmcnt(0)" ::: "memory");
;   __syncthreads();
;   if (otid() == 0) {
;     __builtin_amdgcn_fence(__ATOMIC_RELEASE, "agent");
;     asm volatile("s_waitcnt vmcnt(0)" ::: "memory");
;     __hip_atomic_fetch_add(ctr, 1u, __ATOMIC_RELAXED, __HIP_MEMORY_SCOPE_AGENT);
; template <class Epi, class Sched>
; __device__ __forceinline__ void gemm_phase(PG8_LAS unsigned char* lds, const Gemm g, const Sched& S, const Epi& E) {
;     ...
;     PG8_WAIT_V(0);
;     if (wr == 0) PG8_BAR;
;     PG8_BAR;
.LBB0_1717:
	s_setprio 0
	s_waitcnt vmcnt(0) lgkmcnt(0)
	s_barrier
	v_readlane_b32 s6, v255, 63
	v_readlane_b32 s7, v249, 7
	v_cmp_eq_u32_e32 vcc, 0, v153
	s_and_saveexec_b64 s[0:1], vcc
	s_cbranch_execz .Ltr_p_arr
	buffer_wbl2 sc1
	s_waitcnt vmcnt(0)
	v_readlane_b32 s2, v249, 44
	v_readlane_b32 s3, v249, 45
	s_lshl_b32 s4, s6, 3
	s_add_u32 s2, s2, s4
	s_addc_u32 s3, s3, 0
	s_nop 4
	global_atomic_add v17, v182, s[2:3]

; #define PG8_STAGE(bufoff, gbase, voff) do { _Pragma("unroll") for (int _i = 0; _i < 2; ++_i) \
;         __builtin_amdgcn_global_load_lds((const unsigned*)((const char*)(gbase) + (voff)[_i]), (PG8_LAS unsigned*)(lds + (bufoff) + ldsw + _i * 8192), 16, 0, 0); } while (0)
; #define PG8_LDA(dst, b, h) do { _Pragma("unroll") for (int m = 0; m < 4; ++m) _Pragma("unroll") for (int k = 0; k < 2; ++k) dst[m][k] = *(const PG8_LAS bf16x8*)(lds + PG8_SA(b, h) + aoff + m * 2048 + k * 1024); } while (0)
; #define PG8_LDB(dst, b, h) do { _Pragma("unroll") for (int n = 0; n < 2; ++n) _Pragma("unroll") for (int k = 0; k < 2; ++k) dst[n][k] = *(const PG8_LAS bf16x8*)(lds + PG8_SB(b, h) + boff + n * 2048 + k * 1024); } while (0)
; #define PG8_MMA(ai, bj, At, Bt) do { __builtin_amdgcn_s_setprio(1); _Pragma("unroll") for (int m = 0; m < 4; ++m) _Pragma("unroll") for (int n = 0; n < 2; ++n) _Pragma("unroll") for (int k = 0; k < 2; ++k) \
;         acc[ai][bj][m][n] = __builtin_amdgcn_mfma_f32_16x16x32_bf16(Bt[n][k], At[m][k], acc[ai][bj][m][n], 0, 0, 0); __builtin_amdgcn_s_setprio(0); } while (0)
; template <class Epi, class Sched>
; __device__ __forceinline__ void gemm_phase(PG8_LAS unsigned char* lds, const Gemm g, const Sched& S, const Epi& E) {
;     ...
;             PG8_LDB(B0, 0, 0); PG8_SCHED; PG8_LDA(At, 0, 0); PG8_STAGE(PG8_SA(1, 1), a1 + hstep, voffA);
;             PG8_WAIT_L(8); PG8_BAR; PG8_WAIT_L(0); PG8_MMA(0, 0, At, B0); PG8_BAR; PG8_SCHED;
;             PG8_LDB(B1, 0, 1); PG8_STAGE(PG8_SB(0, 0), b2, voffB);
;             PG8_BAR; PG8_WAIT_L(0); PG8_MMA(0, 1, At, B1); PG8_BAR;
;             PG8_LDA(At, 0, 1); PG8_STAGE(PG8_SA(0, 0), a2, voffA);
;             PG8_BAR; PG8_WAIT_L(0); PG8_MMA(1, 0, At, B0); PG8_BAR; PG8_SCHED;
;             PG8_STAGE(PG8_SB(0, 1), b2 + hstep, voffB);
;             PG8_WAIT_V(6); PG8_BAR; PG8_MMA(1, 1, At, B1); PG8_BAR;
;             PG8_LDB(B0, 1, 0); PG8_SCHED; PG8_LDA(At, 1, 0); PG8_STAGE(PG8_SA(0, 1), a2 + hstep, voffA);
;             PG8_WAIT_L(8); PG8_BAR; PG8_WAIT_L(0); PG8_MMA(0, 0, At, B0); PG8_BAR; PG8_SCHED;
;             PG8_LDB(B1, 1, 1); PG8_STAGE(PG8_SB(1, 0), b3, voffB);
;             PG8_BAR; PG8_WAIT_L(0); PG8_MMA(0, 1, At, B1); PG8_BAR;
;             PG8_LDA(At, 1, 1); PG8_STAGE(PG8_SA(1, 0), a3, voffA);
;             PG8_BAR; PG8_WAIT_L(0); PG8_MMA(1, 0, At, B0); PG8_BAR; PG8_SCHED;
.LBB0_2735:
	s_add_u32 s16, s12, s14
	s_addc_u32 s17, s13, s15
	s_add_u32 s16, s16, 0x100
	s_addc_u32 s17, s17, 0
	s_add_u32 s33, s39, s14
	s_addc_u32 s42, s40, s15
	s_cmpk_eq_i32 s14, 0x700
	s_cselect_b32 s19, s5, s17
	s_cselect_b32 s18, s36, s16
	s_cselect_b32 s17, s37, s42
	s_cselect_b32 s16, s38, s33
	s_add_i32 s33, 0, 0x10000
	v_add_u32_e32 v16, s33, v139
	ds_read_b128 v[178:181], v16
	ds_read_b128 v[188:191], v16 offset:1024
	ds_read_b128 v[192:195], v16 offset:2048
	ds_read_b128 v[196:199], v16 offset:3072
	v_lshl_add_u64 v[18:19], v[162:163], 0, s[14:15]
	s_add_i32 m0, s25, 0xc000
	ds_read_b128 v[200:203], v171
	ds_read_b128 v[204:207], v171 offset:1024
	ds_read_b128 v[208:211], v171 offset:2048
	ds_read_b128 v[212:215], v171 offset:3072
	ds_read_b128 v[216:219], v171 offset:4096
	ds_read_b128 v[220:223], v171 offset:5120
	ds_read_b128 v[224:227], v171 offset:6144
	ds_read_b128 v[228:231], v171 offset:7168
	global_load_lds_dwordx4 v[18:19], off
	v_lshl_add_u64 v[18:19], v[164:165], 0, s[14:15]
	s_add_i32 m0, s25, 0xe000
	s_nop 0
	global_load_lds_dwordx4 v[18:19], off
	s_waitcnt lgkmcnt(8)
	s_barrier
	s_waitcnt lgkmcnt(0)
	s_waitcnt lgkmcnt(0)
	v_mfma_f32_16x16x32_bf16 v[130:133], v[178:181], v[200:203], v[130:133]
	v_mfma_f32_16x16x32_bf16 v[126:129], v[192:195], v[200:203], v[126:129]
	v_mfma_f32_16x16x32_bf16 v[114:117], v[178:181], v[208:211], v[114:117]
	v_mfma_f32_16x16x32_bf16 v[110:113], v[192:195], v[208:211], v[110:113]
	v_mfma_f32_16x16x32_bf16 v[98:101], v[178:181], v[216:219], v[98:101]
	v_mfma_f32_16x16x32_bf16 v[94:97], v[192:195], v[216:219], v[94:97]
	v_mfma_f32_16x16x32_bf16 v[82:85], v[178:181], v[224:227], v[82:85]
	v_mfma_f32_16x16x32_bf16 v[78:81], v[192:195], v[224:227], v[78:81]
	v_mfma_f32_16x16x32_bf16 v[130:133], v[188:191], v[204:207], v[130:133]
	v_mfma_f32_16x16x32_bf16 v[126:129], v[196:199], v[204:207], v[126:129]
	v_mfma_f32_16x16x32_bf16 v[114:117], v[188:191], v[212:215], v[114:117]
	v_mfma_f32_16x16x32_bf16 v[110:113], v[196:199], v[212:215], v[110:113]
	v_mfma_f32_16x16x32_bf16 v[98:101], v[188:191], v[220:223], v[98:101]
	v_mfma_f32_16x16x32_bf16 v[94:97], v[196:199], v[220:223], v[94:97]
	v_mfma_f32_16x16x32_bf16 v[82:85], v[188:191], v[228:231], v[82:85]
	v_mfma_f32_16x16x32_bf16 v[78:81], v[196:199], v[228:231], v[78:81]
	s_barrier
	s_add_i32 s44, 0, 0x14000
	s_add_i32 s33, s33, s23
	v_add_u32_e32 v16, s44, v139
	v_lshl_add_u64 v[18:19], s[16:17], 0, v[136:137]
	s_mov_b32 m0, s33
	ds_read_b128 v[232:235], v16
	ds_read_b128 v[236:239], v16 offset:1024
	ds_read_b128 v[240:243], v16 offset:2048
	ds_read_b128 v[244:247], v16 offset:3072
	global_load_lds_dwordx4 v[18:19], off
	v_lshl_add_u64 v[186:187], s[16:17], 0, v[134:135]
	s_add_i32 m0, s33, 0x2000
	s_nop 0
	global_load_lds_dwordx4 v[186:187], off
	s_barrier
	s_waitcnt lgkmcnt(0)
	s_waitcnt lgkmcnt(0)
	v_mfma_f32_16x16x32_bf16 v[122:125], v[232:235], v[200:203], v[122:125]
	v_mfma_f32_16x16x32_bf16 v[118:121], v[240:243], v[200:203], v[118:121]
	v_mfma_f32_16x16x32_bf16 v[106:109], v[232:235], v[208:211], v[106:109]
	v_mfma_f32_16x16x32_bf16 v[102:105], v[240:243], v[208:211], v[102:105]
	v_mfma_f32_16x16x32_bf16 v[90:93], v[232:235], v[216:219], v[90:93]
	v_mfma_f32_16x16x32_bf16 v[86:89], v[240:243], v[216:219], v[86:89]
	v_mfma_f32_16x16x32_bf16 v[74:77], v[232:235], v[224:227], v[74:77]
	v_mfma_f32_16x16x32_bf16 v[70:73], v[240:243], v[224:227], v[70:73]
	v_mfma_f32_16x16x32_bf16 v[122:125], v[236:239], v[204:207], v[122:125]
	v_mfma_f32_16x16x32_bf16 v[118:121], v[244:247], v[204:207], v[118:121]
	v_mfma_f32_16x16x32_bf16 v[106:109], v[236:239], v[212:215], v[106:109]
	v_mfma_f32_16x16x32_bf16 v[102:105], v[244:247], v[212:215], v[102:105]
	v_mfma_f32_16x16x32_bf16 v[90:93], v[236:239], v[220:223], v[90:93]
	v_mfma_f32_16x16x32_bf16 v[86:89], v[244:247], v[220:223], v[86:89]
	v_mfma_f32_16x16x32_bf16 v[74:77], v[236:239], v[228:231], v[74:77]
	v_mfma_f32_16x16x32_bf16 v[70:73], v[244:247], v[228:231], v[70:73]
	s_mov_b32 m0, s25
	v_lshl_add_u64 v[154:155], s[18:19], 0, v[136:137]
	s_barrier
	ds_read_b128 v[200:203], v171 offset:16384
	ds_read_b128 v[204:207], v171 offset:17408
	ds_read_b128 v[208:211], v171 offset:18432
	ds_read_b128 v[212:215], v171 offset:19456
	ds_read_b128 v[216:219], v171 offset:20480
	ds_read_b128 v[220:223], v171 offset:21504
	ds_read_b128 v[224:227], v171 offset:22528
	ds_read_b128 v[228:231], v171 offset:23552
	global_load_lds_dwordx4 v[154:155], off
	v_lshl_add_u64 v[156:157], s[18:19], 0, v[134:135]
	s_mov_b32 m0, s26
	s_nop 0
	global_load_lds_dwordx4 v[156:157], off
	s_barrier
	s_waitcnt lgkmcnt(0)
	s_waitcnt lgkmcnt(0)
	v_mfma_f32_16x16x32_bf16 v[66:69], v[178:181], v[200:203], v[66:69]
	v_mfma_f32_16x16x32_bf16 v[62:65], v[192:195], v[200:203], v[62:65]
	v_mfma_f32_16x16x32_bf16 v[50:53], v[178:181], v[208:211], v[50:53]
	v_mfma_f32_16x16x32_bf16 v[46:49], v[192:195], v[208:211], v[46:49]
	v_mfma_f32_16x16x32_bf16 v[34:37], v[178:181], v[216:219], v[34:37]
	v_mfma_f32_16x16x32_bf16 v[30:33], v[192:195], v[216:219], v[30:33]
	v_mfma_f32_16x16x32_bf16 v[12:15], v[178:181], v[224:227], v[12:15]
	v_mfma_f32_16x16x32_bf16 v[8:11], v[192:195], v[224:227], v[8:11]
	v_mfma_f32_16x16x32_bf16 v[66:69], v[188:191], v[204:207], v[66:69]
	v_mfma_f32_16x16x32_bf16 v[62:65], v[196:199], v[204:207], v[62:65]
	v_mfma_f32_16x16x32_bf16 v[50:53], v[188:191], v[212:215], v[50:53]
	v_mfma_f32_16x16x32_bf16 v[46:49], v[196:199], v[212:215], v[46:49]
	v_mfma_f32_16x16x32_bf16 v[34:37], v[188:191], v[220:223], v[34:37]
	v_mfma_f32_16x16x32_bf16 v[30:33], v[196:199], v[220:223], v[30:33]
	v_mfma_f32_16x16x32_bf16 v[12:15], v[188:191], v[228:231], v[12:15]
	v_mfma_f32_16x16x32_bf16 v[8:11], v[196:199], v[228:231], v[8:11]
	s_barrier
; #define PG8_STAGE(bufoff, gbase, voff) do { _Pragma("unroll") for (int _i = 0; _i < 2; ++_i) \
;         __builtin_amdgcn_global_load_lds((const unsigned*)((const char*)(gbase) + (voff)[_i]), (PG8_LAS unsigned*)(lds + (bufoff) + ldsw + _i * 8192), 16, 0, 0); } while (0)
; #define PG8_LDA(dst, b, h) do { _Pragma("unroll") for (int m = 0; m < 4; ++m) _Pragma("unroll") for (int k = 0; k < 2; ++k) dst[m][k] = *(const PG8_LAS bf16x8*)(lds + PG8_SA(b, h) + aoff + m * 2048 + k * 1024); } while (0)
; #define PG8_LDB(dst, b, h) do { _Pragma("unroll") for (int n = 0; n < 2; ++n) _Pragma("unroll") for (int k = 0; k < 2; ++k) dst[n][k] = *(const PG8_LAS bf16x8*)(lds + PG8_SB(b, h) + boff + n * 2048 + k * 1024); } while (0)
; #define PG8_MMA(ai, bj, At, Bt) do { __builtin_amdgcn_s_setprio(1); _Pragma("unroll") for (int m = 0; m < 4; ++m) _Pragma("unroll") for (int n = 0; n < 2; ++n) _Pragma("unroll") for (int k = 0; k < 2; ++k) \
;         acc[ai][bj][m][n] = __builtin_amdgcn_mfma_f32_16x16x32_bf16(Bt[n][k], At[m][k], acc[ai][bj][m][n], 0, 0, 0); __builtin_amdgcn_s_setprio(0); } while (0)
; #define PG8_WAIT_V(n) asm volatile("s_waitcnt vmcnt(" #n ")" ::: "memory")
; #define PG8_WAIT_L(n) asm volatile("s_waitcnt lgkmcnt(" #n ")" ::: "memory")
; #define PG8_BAR __builtin_amdgcn_s_barrier()
; #define PG8_SCHED __builtin_amdgcn_sched_barrier(0)
; template <class Epi, class Sched>
; __device__ __forceinline__ void gemm_phase(PG8_LAS unsigned char* lds, const Gemm g, const Sched& S, const Epi& E) {
;     ...
;             PG8_BAR; PG8_WAIT_L(0); PG8_MMA(1, 0, At, B0); PG8_BAR; PG8_SCHED;
;             PG8_STAGE(PG8_SB(0, 1), b2 + hstep, voffB);
;             PG8_WAIT_V(6); PG8_BAR; PG8_MMA(1, 1, At, B1); PG8_BAR;
;             PG8_LDB(B0, 1, 0); PG8_SCHED; PG8_LDA(At, 1, 0); PG8_STAGE(PG8_SA(0, 1), a2 + hstep, voffA);
;             PG8_WAIT_L(8); PG8_BAR; PG8_WAIT_L(0); PG8_MMA(0, 0, At, B0); PG8_BAR; PG8_SCHED;
;             PG8_LDB(B1, 1, 1); PG8_STAGE(PG8_SB(1, 0), b3, voffB);
;             PG8_BAR; PG8_WAIT_L(0); PG8_MMA(0, 1, At, B1); PG8_BAR;
;             PG8_LDA(At, 1, 1); PG8_STAGE(PG8_SA(1, 0), a3, voffA);
;             PG8_BAR; PG8_WAIT_L(0); PG8_MMA(1, 0, At, B0); PG8_BAR; PG8_SCHED;
	s_add_u32 s42, s16, 0x40000
	s_addc_u32 s43, s17, 0
	s_add_i32 s33, s44, s23
	v_lshl_add_u64 v[178:179], s[42:43], 0, v[136:137]
	s_mov_b32 m0, s33
	s_nop 0
	global_load_lds_dwordx4 v[178:179], off
	v_lshl_add_u64 v[178:179], s[42:43], 0, v[134:135]
	s_add_i32 m0, s33, 0x2000
	s_nop 0
	global_load_lds_dwordx4 v[178:179], off
	s_waitcnt vmcnt(6)
	s_barrier
	v_mfma_f32_16x16x32_bf16 v[58:61], v[232:235], v[200:203], v[58:61]
	v_mfma_f32_16x16x32_bf16 v[54:57], v[240:243], v[200:203], v[54:57]
	v_mfma_f32_16x16x32_bf16 v[42:45], v[232:235], v[208:211], v[42:45]
	v_mfma_f32_16x16x32_bf16 v[38:41], v[240:243], v[208:211], v[38:41]
	v_mfma_f32_16x16x32_bf16 v[26:29], v[232:235], v[216:219], v[26:29]
	v_mfma_f32_16x16x32_bf16 v[22:25], v[240:243], v[216:219], v[22:25]
	v_mfma_f32_16x16x32_bf16 v[4:7], v[232:235], v[224:227], v[4:7]
	v_mfma_f32_16x16x32_bf16 v[0:3], v[240:243], v[224:227], v[0:3]
	v_mfma_f32_16x16x32_bf16 v[58:61], v[236:239], v[204:207], v[58:61]
	v_mfma_f32_16x16x32_bf16 v[54:57], v[244:247], v[204:207], v[54:57]
	v_mfma_f32_16x16x32_bf16 v[42:45], v[236:239], v[212:215], v[42:45]
	v_mfma_f32_16x16x32_bf16 v[38:41], v[244:247], v[212:215], v[38:41]
	v_mfma_f32_16x16x32_bf16 v[26:29], v[236:239], v[220:223], v[26:29]
	v_mfma_f32_16x16x32_bf16 v[22:25], v[244:247], v[220:223], v[22:25]
	v_mfma_f32_16x16x32_bf16 v[4:7], v[236:239], v[228:231], v[4:7]
	v_mfma_f32_16x16x32_bf16 v[0:3], v[244:247], v[228:231], v[0:3]
	s_add_i32 s33, 0, 0x18000
	v_add_u32_e32 v16, s33, v139
	s_barrier
	ds_read_b128 v[178:181], v16
	ds_read_b128 v[188:191], v16 offset:1024
	ds_read_b128 v[192:195], v16 offset:2048
	ds_read_b128 v[196:199], v16 offset:3072
	s_add_u32 s18, s18, 0x40000
	s_addc_u32 s19, s19, 0
	s_mov_b32 m0, s27
	v_lshl_add_u64 v[232:233], s[18:19], 0, v[136:137]
	ds_read_b128 v[200:203], v171 offset:32768
	ds_read_b128 v[204:207], v171 offset:33792
	ds_read_b128 v[208:211], v171 offset:34816
	ds_read_b128 v[212:215], v171 offset:35840
	ds_read_b128 v[216:219], v171 offset:36864
	ds_read_b128 v[220:223], v171 offset:37888
	ds_read_b128 v[224:227], v171 offset:38912
	ds_read_b128 v[228:231], v171 offset:39936
	global_load_lds_dwordx4 v[232:233], off
	v_lshl_add_u64 v[232:233], s[18:19], 0, v[134:135]
	s_mov_b32 m0, s28
	s_nop 0
	global_load_lds_dwordx4 v[232:233], off
	s_waitcnt lgkmcnt(8)
	s_barrier
	s_waitcnt lgkmcnt(0)
	s_waitcnt lgkmcnt(0)
	v_mfma_f32_16x16x32_bf16 v[130:133], v[178:181], v[200:203], v[130:133]
	v_mfma_f32_16x16x32_bf16 v[126:129], v[192:195], v[200:203], v[126:129]
	v_mfma_f32_16x16x32_bf16 v[114:117], v[178:181], v[208:211], v[114:117]
	v_mfma_f32_16x16x32_bf16 v[110:113], v[192:195], v[208:211], v[110:113]
	v_mfma_f32_16x16x32_bf16 v[98:101], v[178:181], v[216:219], v[98:101]
	v_mfma_f32_16x16x32_bf16 v[94:97], v[192:195], v[216:219], v[94:97]
	v_mfma_f32_16x16x32_bf16 v[82:85], v[178:181], v[224:227], v[82:85]
	v_mfma_f32_16x16x32_bf16 v[78:81], v[192:195], v[224:227], v[78:81]
	v_mfma_f32_16x16x32_bf16 v[130:133], v[188:191], v[204:207], v[130:133]
	v_mfma_f32_16x16x32_bf16 v[126:129], v[196:199], v[204:207], v[126:129]
	v_mfma_f32_16x16x32_bf16 v[114:117], v[188:191], v[212:215], v[114:117]
	v_mfma_f32_16x16x32_bf16 v[110:113], v[196:199], v[212:215], v[110:113]
	v_mfma_f32_16x16x32_bf16 v[98:101], v[188:191], v[220:223], v[98:101]
	v_mfma_f32_16x16x32_bf16 v[94:97], v[196:199], v[220:223], v[94:97]
	v_mfma_f32_16x16x32_bf16 v[82:85], v[188:191], v[228:231], v[82:85]
	v_mfma_f32_16x16x32_bf16 v[78:81], v[196:199], v[228:231], v[78:81]
	s_barrier
	s_add_i32 s18, 0, 0x1c000
	s_mov_b64 s[42:43], 0x80
	s_add_i32 s19, s33, s23
	v_add_u32_e32 v16, s18, v139
	v_lshl_add_u64 v[18:19], v[18:19], 0, s[42:43]
	s_mov_b32 m0, s19
	ds_read_b128 v[232:235], v16
	ds_read_b128 v[236:239], v16 offset:1024
	ds_read_b128 v[240:243], v16 offset:2048
	ds_read_b128 v[244:247], v16 offset:3072
	global_load_lds_dwordx4 v[18:19], off
	v_lshl_add_u64 v[18:19], v[186:187], 0, s[42:43]
	s_add_i32 m0, s19, 0x2000
	s_nop 0
	global_load_lds_dwordx4 v[18:19], off
	s_barrier
; #define PG8_STAGE(bufoff, gbase, voff) do { _Pragma("unroll") for (int _i = 0; _i < 2; ++_i) \
;         __builtin_amdgcn_global_load_lds((const unsigned*)((const char*)(gbase) + (voff)[_i]), (PG8_LAS unsigned*)(lds + (bufoff) + ldsw + _i * 8192), 16, 0, 0); } while (0)
; #define PG8_LDA(dst, b, h) do { _Pragma("unroll") for (int m = 0; m < 4; ++m) _Pragma("unroll") for (int k = 0; k < 2; ++k) dst[m][k] = *(const PG8_LAS bf16x8*)(lds + PG8_SA(b, h) + aoff + m * 2048 + k * 1024); } while (0)
; #define PG8_LDB(dst, b, h) do { _Pragma("unroll") for (int n = 0; n < 2; ++n) _Pragma("unroll") for (int k = 0; k < 2; ++k) dst[n][k] = *(const PG8_LAS bf16x8*)(lds + PG8_SB(b, h) + boff + n * 2048 + k * 1024); } while (0)
; #define PG8_MMA(ai, bj, At, Bt) do { __builtin_amdgcn_s_setprio(1); _Pragma("unroll") for (int m = 0; m < 4; ++m) _Pragma("unroll") for (int n = 0; n < 2; ++n) _Pragma("unroll") for (int k = 0; k < 2; ++k) \
;         acc[ai][bj][m][n] = __builtin_amdgcn_mfma_f32_16x16x32_bf16(Bt[n][k], At[m][k], acc[ai][bj][m][n], 0, 0, 0); __builtin_amdgcn_s_setprio(0); } while (0)
; #define PG8_WAIT_V(n) asm volatile("s_waitcnt vmcnt(" #n ")" ::: "memory")
; #define PG8_WAIT_L(n) asm volatile("s_waitcnt lgkmcnt(" #n ")" ::: "memory")
; #define PG8_BAR __builtin_amdgcn_s_barrier()
; #define PG8_SCHED __builtin_amdgcn_sched_barrier(0)
; template <class Epi, class Sched>
; __device__ __forceinline__ void gemm_phase(PG8_LAS unsigned char* lds, const Gemm g, const Sched& S, const Epi& E) {
;     ...
;             PG8_BAR; PG8_WAIT_L(0); PG8_MMA(1, 0, At, B0); PG8_BAR; PG8_SCHED;
;             PG8_STAGE(PG8_SB(0, 1), b2 + hstep, voffB);
;             PG8_WAIT_V(6); PG8_BAR; PG8_MMA(1, 1, At, B1); PG8_BAR;
;             PG8_LDB(B0, 1, 0); PG8_SCHED; PG8_LDA(At, 1, 0); PG8_STAGE(PG8_SA(0, 1), a2 + hstep, voffA);
;             PG8_WAIT_L(8); PG8_BAR; PG8_WAIT_L(0); PG8_MMA(0, 0, At, B0); PG8_BAR; PG8_SCHED;
;             PG8_LDB(B1, 1, 1); PG8_STAGE(PG8_SB(1, 0), b3, voffB);
;             PG8_BAR; PG8_WAIT_L(0); PG8_MMA(0, 1, At, B1); PG8_BAR;
;             PG8_LDA(At, 1, 1); PG8_STAGE(PG8_SA(1, 0), a3, voffA);
;             PG8_BAR; PG8_WAIT_L(0); PG8_MMA(1, 0, At, B0); PG8_BAR; PG8_SCHED;
;             PG8_STAGE(PG8_SB(1, 1), b3 + hstep, voffB);
;             PG8_WAIT_V(6); PG8_BAR; PG8_MMA(1, 1, At, B1); PG8_BAR;
	s_waitcnt lgkmcnt(0)
	s_waitcnt lgkmcnt(0)
	v_mfma_f32_16x16x32_bf16 v[122:125], v[232:235], v[200:203], v[122:125]
	v_mfma_f32_16x16x32_bf16 v[118:121], v[240:243], v[200:203], v[118:121]
	v_mfma_f32_16x16x32_bf16 v[106:109], v[232:235], v[208:211], v[106:109]
	v_mfma_f32_16x16x32_bf16 v[102:105], v[240:243], v[208:211], v[102:105]
	v_mfma_f32_16x16x32_bf16 v[90:93], v[232:235], v[216:219], v[90:93]
	v_mfma_f32_16x16x32_bf16 v[86:89], v[240:243], v[216:219], v[86:89]
	v_mfma_f32_16x16x32_bf16 v[74:77], v[232:235], v[224:227], v[74:77]
	v_mfma_f32_16x16x32_bf16 v[70:73], v[240:243], v[224:227], v[70:73]
	v_mfma_f32_16x16x32_bf16 v[122:125], v[236:239], v[204:207], v[122:125]
	v_mfma_f32_16x16x32_bf16 v[118:121], v[244:247], v[204:207], v[118:121]
	v_mfma_f32_16x16x32_bf16 v[106:109], v[236:239], v[212:215], v[106:109]
	v_mfma_f32_16x16x32_bf16 v[102:105], v[244:247], v[212:215], v[102:105]
	v_mfma_f32_16x16x32_bf16 v[90:93], v[236:239], v[220:223], v[90:93]
	v_mfma_f32_16x16x32_bf16 v[86:89], v[244:247], v[220:223], v[86:89]
	v_mfma_f32_16x16x32_bf16 v[74:77], v[236:239], v[228:231], v[74:77]
	v_mfma_f32_16x16x32_bf16 v[70:73], v[244:247], v[228:231], v[70:73]
	s_mov_b32 m0, s30
	v_lshl_add_u64 v[18:19], v[154:155], 0, s[42:43]
	s_barrier
	ds_read_b128 v[200:203], v171 offset:49152
	ds_read_b128 v[204:207], v171 offset:50176
	ds_read_b128 v[208:211], v171 offset:51200
	ds_read_b128 v[212:215], v171 offset:52224
	ds_read_b128 v[216:219], v171 offset:53248
	ds_read_b128 v[220:223], v171 offset:54272
	ds_read_b128 v[224:227], v171 offset:55296
	ds_read_b128 v[228:231], v171 offset:56320
	global_load_lds_dwordx4 v[18:19], off
	v_lshl_add_u64 v[18:19], v[156:157], 0, s[42:43]
	s_mov_b32 m0, s31
	s_nop 0
	global_load_lds_dwordx4 v[18:19], off
	s_barrier
	s_waitcnt lgkmcnt(0)
	s_waitcnt lgkmcnt(0)
	v_mfma_f32_16x16x32_bf16 v[66:69], v[178:181], v[200:203], v[66:69]
	v_mfma_f32_16x16x32_bf16 v[62:65], v[192:195], v[200:203], v[62:65]
	v_mfma_f32_16x16x32_bf16 v[50:53], v[178:181], v[208:211], v[50:53]
	v_mfma_f32_16x16x32_bf16 v[46:49], v[192:195], v[208:211], v[46:49]
	v_mfma_f32_16x16x32_bf16 v[34:37], v[178:181], v[216:219], v[34:37]
	v_mfma_f32_16x16x32_bf16 v[30:33], v[192:195], v[216:219], v[30:33]
	v_mfma_f32_16x16x32_bf16 v[12:15], v[178:181], v[224:227], v[12:15]
	v_mfma_f32_16x16x32_bf16 v[8:11], v[192:195], v[224:227], v[8:11]
	v_mfma_f32_16x16x32_bf16 v[66:69], v[188:191], v[204:207], v[66:69]
	v_mfma_f32_16x16x32_bf16 v[62:65], v[196:199], v[204:207], v[62:65]
	v_mfma_f32_16x16x32_bf16 v[50:53], v[188:191], v[212:215], v[50:53]
	v_mfma_f32_16x16x32_bf16 v[46:49], v[196:199], v[212:215], v[46:49]
	v_mfma_f32_16x16x32_bf16 v[34:37], v[188:191], v[220:223], v[34:37]
	v_mfma_f32_16x16x32_bf16 v[30:33], v[196:199], v[220:223], v[30:33]
	v_mfma_f32_16x16x32_bf16 v[12:15], v[188:191], v[228:231], v[12:15]
	v_mfma_f32_16x16x32_bf16 v[8:11], v[196:199], v[228:231], v[8:11]
	s_barrier
	s_add_u32 s16, s16, 0x40080
	s_addc_u32 s17, s17, 0
	s_add_i32 s18, s18, s23
	v_lshl_add_u64 v[18:19], s[16:17], 0, v[136:137]
	s_mov_b32 m0, s18
	s_nop 0
	global_load_lds_dwordx4 v[18:19], off
	v_lshl_add_u64 v[18:19], s[16:17], 0, v[134:135]
	s_add_i32 m0, s18, 0x2000
	s_nop 0
	global_load_lds_dwordx4 v[18:19], off
	s_waitcnt vmcnt(6)
	s_barrier
	v_mfma_f32_16x16x32_bf16 v[58:61], v[232:235], v[200:203], v[58:61]
	v_mfma_f32_16x16x32_bf16 v[54:57], v[240:243], v[200:203], v[54:57]
	v_mfma_f32_16x16x32_bf16 v[42:45], v[232:235], v[208:211], v[42:45]
	v_mfma_f32_16x16x32_bf16 v[38:41], v[240:243], v[208:211], v[38:41]
	v_mfma_f32_16x16x32_bf16 v[26:29], v[232:235], v[216:219], v[26:29]
	v_mfma_f32_16x16x32_bf16 v[22:25], v[240:243], v[216:219], v[22:25]
	v_mfma_f32_16x16x32_bf16 v[4:7], v[232:235], v[224:227], v[4:7]
	v_mfma_f32_16x16x32_bf16 v[0:3], v[240:243], v[224:227], v[0:3]
	v_mfma_f32_16x16x32_bf16 v[58:61], v[236:239], v[204:207], v[58:61]
	v_mfma_f32_16x16x32_bf16 v[54:57], v[244:247], v[204:207], v[54:57]
	v_mfma_f32_16x16x32_bf16 v[42:45], v[236:239], v[212:215], v[42:45]
	v_mfma_f32_16x16x32_bf16 v[38:41], v[244:247], v[212:215], v[38:41]
	v_mfma_f32_16x16x32_bf16 v[26:29], v[236:239], v[220:223], v[26:29]
	v_mfma_f32_16x16x32_bf16 v[22:25], v[244:247], v[220:223], v[22:25]
	v_mfma_f32_16x16x32_bf16 v[4:7], v[236:239], v[228:231], v[4:7]
	v_mfma_f32_16x16x32_bf16 v[0:3], v[244:247], v[228:231], v[0:3]
	s_add_i32 s41, s41, 2
	s_add_u32 s14, s14, 0x100
	s_addc_u32 s15, s15, 0
	s_cmp_gt_u32 s41, 13
	s_barrier
	s_cbranch_scc1 .LBB0_2731

; DI int otid() { int t = threadIdx.x; asm volatile("" : "+v"(t)); return t; }
; #define PG8_WAIT_V(n) asm volatile("s_waitcnt vmcnt(" #n ")" ::: "memory")
; #define PG8_BAR __builtin_amdgcn_s_barrier()
; DI void gbar(unsigned* ctr, unsigned target) {
;   asm volatile("s_waitcnt vmcnt(0)" ::: "memory");
;   __syncthreads();
;   if (otid() == 0) {
;     __builtin_amdgcn_fence(__ATOMIC_RELEASE, "agent");
;     asm volatile("s_waitcnt vmcnt(0)" ::: "memory");
;     __hip_atomic_fetch_add(ctr, 1u, __ATOMIC_RELAXED, __HIP_MEMORY_SCOPE_AGENT);
; template <class Epi, class Sched>
; __device__ __forceinline__ void gemm_phase(PG8_LAS unsigned char* lds, const Gemm g, const Sched& S, const Epi& E) {
;     ...
;     PG8_WAIT_V(0);
;     if (wr == 0) PG8_BAR;
;     PG8_BAR;
.LBB0_2741:
	s_setprio 0
	s_waitcnt vmcnt(0)
	s_waitcnt lgkmcnt(0)
	s_barrier
	v_readlane_b32 s6, v255, 63
	v_readlane_b32 s7, v249, 7
	v_cmp_eq_u32_e32 vcc, 0, v153
	s_and_saveexec_b64 s[0:1], vcc
	s_cbranch_execz .Ltr_m_arr
	buffer_wbl2 sc1
	s_waitcnt vmcnt(0)
	v_readlane_b32 s2, v249, 44
	v_readlane_b32 s3, v249, 45
	s_lshl_b32 s4, s6, 2
	s_add_u32 s2, s2, s4
	s_addc_u32 s3, s3, 0
	s_nop 4
	global_atomic_add v17, v182, s[2:3]

.Lstg_out_done:
.Ltr_o_reenter:
	v_readfirstlane_b32 s0, v153
	s_cmpk_gt_u32 s0, 0xff
	s_cbranch_scc0 .Lprio_o
	s_setprio 1

; #define PG8_STAGE(bufoff, gbase, voff) do { _Pragma("unroll") for (int _i = 0; _i < 2; ++_i) \
;         __builtin_amdgcn_global_load_lds((const unsigned*)((const char*)(gbase) + (voff)[_i]), (PG8_LAS unsigned*)(lds + (bufoff) + ldsw + _i * 8192), 16, 0, 0); } while (0)
; #define PG8_LDA(dst, b, h) do { _Pragma("unroll") for (int m = 0; m < 4; ++m) _Pragma("unroll") for (int k = 0; k < 2; ++k) dst[m][k] = *(const PG8_LAS bf16x8*)(lds + PG8_SA(b, h) + aoff + m * 2048 + k * 1024); } while (0)
; #define PG8_LDB(dst, b, h) do { _Pragma("unroll") for (int n = 0; n < 2; ++n) _Pragma("unroll") for (int k = 0; k < 2; ++k) dst[n][k] = *(const PG8_LAS bf16x8*)(lds + PG8_SB(b, h) + boff + n * 2048 + k * 1024); } while (0)
; #define PG8_MMA(ai, bj, At, Bt) do { __builtin_amdgcn_s_setprio(1); _Pragma("unroll") for (int m = 0; m < 4; ++m) _Pragma("unroll") for (int n = 0; n < 2; ++n) _Pragma("unroll") for (int k = 0; k < 2; ++k) \
;         acc[ai][bj][m][n] = __builtin_amdgcn_mfma_f32_16x16x32_bf16(Bt[n][k], At[m][k], acc[ai][bj][m][n], 0, 0, 0); __builtin_amdgcn_s_setprio(0); } while (0)
; template <class Epi, class Sched>
; __device__ __forceinline__ void gemm_phase(PG8_LAS unsigned char* lds, const Gemm g, const Sched& S, const Epi& E) {
;     ...
;             PG8_LDB(B0, 0, 0); PG8_SCHED; PG8_LDA(At, 0, 0); PG8_STAGE(PG8_SA(1, 1), a1 + hstep, voffA);
;             PG8_WAIT_L(8); PG8_BAR; PG8_WAIT_L(0); PG8_MMA(0, 0, At, B0); PG8_BAR; PG8_SCHED;
;             PG8_LDB(B1, 0, 1); PG8_STAGE(PG8_SB(0, 0), b2, voffB);
;             PG8_BAR; PG8_WAIT_L(0); PG8_MMA(0, 1, At, B1); PG8_BAR;
;             PG8_LDA(At, 0, 1); PG8_STAGE(PG8_SA(0, 0), a2, voffA);
;             PG8_BAR; PG8_WAIT_L(0); PG8_MMA(1, 0, At, B0); PG8_BAR; PG8_SCHED;
;             PG8_STAGE(PG8_SB(0, 1), b2 + hstep, voffB);
;             PG8_WAIT_V(6); PG8_BAR; PG8_MMA(1, 1, At, B1); PG8_BAR;
;             PG8_LDB(B0, 1, 0); PG8_SCHED; PG8_LDA(At, 1, 0); PG8_STAGE(PG8_SA(0, 1), a2 + hstep, voffA);
;             PG8_WAIT_L(8); PG8_BAR; PG8_WAIT_L(0); PG8_MMA(0, 0, At, B0); PG8_BAR; PG8_SCHED;
;             PG8_LDB(B1, 1, 1); PG8_STAGE(PG8_SB(1, 0), b3, voffB);
;             PG8_BAR; PG8_WAIT_L(0); PG8_MMA(0, 1, At, B1); PG8_BAR;
;             PG8_LDA(At, 1, 1); PG8_STAGE(PG8_SA(1, 0), a3, voffA);
;             PG8_BAR; PG8_WAIT_L(0); PG8_MMA(1, 0, At, B0); PG8_BAR; PG8_SCHED;
.LBB0_2754:
	s_add_u32 s14, s12, 0xfffc0080
	s_addc_u32 s15, s13, -1
	s_add_i32 s37, 0, 0x10000
	v_add_u32_e32 v140, s37, v142
	ds_read_b128 v[144:147], v140
	ds_read_b128 v[148:151], v140 offset:1024
	ds_read_b128 v[162:165], v140 offset:2048
	ds_read_b128 v[166:169], v140 offset:3072
	s_cmp_eq_u32 s36, 12
	s_cselect_b32 s17, s5, s15
	s_cselect_b32 s16, s31, s14
	s_cselect_b32 s15, s3, s35
	s_cselect_b32 s14, s33, s34
	v_lshl_add_u64 v[140:141], s[12:13], 0, v[136:137]
	s_add_i32 m0, s23, 0xc000
	ds_read_b128 v[170:173], v143
	ds_read_b128 v[174:177], v143 offset:1024
	ds_read_b128 v[178:181], v143 offset:2048
	ds_read_b128 v[188:191], v143 offset:3072
	ds_read_b128 v[192:195], v143 offset:4096
	ds_read_b128 v[196:199], v143 offset:5120
	ds_read_b128 v[200:203], v143 offset:6144
	ds_read_b128 v[204:207], v143 offset:7168
	global_load_lds_dwordx4 v[140:141], off
	v_lshl_add_u64 v[140:141], s[12:13], 0, v[138:139]
	s_add_i32 m0, s23, 0xe000
	s_nop 0
	global_load_lds_dwordx4 v[140:141], off
	s_waitcnt lgkmcnt(8)
	s_barrier
	s_waitcnt lgkmcnt(0)
	s_waitcnt lgkmcnt(0)
	v_mfma_f32_16x16x32_bf16 v[130:133], v[144:147], v[170:173], v[130:133]
	v_mfma_f32_16x16x32_bf16 v[126:129], v[162:165], v[170:173], v[126:129]
	v_mfma_f32_16x16x32_bf16 v[114:117], v[144:147], v[178:181], v[114:117]
	v_mfma_f32_16x16x32_bf16 v[110:113], v[162:165], v[178:181], v[110:113]
	v_mfma_f32_16x16x32_bf16 v[98:101], v[144:147], v[192:195], v[98:101]
	v_mfma_f32_16x16x32_bf16 v[94:97], v[162:165], v[192:195], v[94:97]
	v_mfma_f32_16x16x32_bf16 v[82:85], v[144:147], v[200:203], v[82:85]
	v_mfma_f32_16x16x32_bf16 v[78:81], v[162:165], v[200:203], v[78:81]
	v_mfma_f32_16x16x32_bf16 v[130:133], v[148:151], v[174:177], v[130:133]
	v_mfma_f32_16x16x32_bf16 v[126:129], v[166:169], v[174:177], v[126:129]
	v_mfma_f32_16x16x32_bf16 v[114:117], v[148:151], v[188:191], v[114:117]
	v_mfma_f32_16x16x32_bf16 v[110:113], v[166:169], v[188:191], v[110:113]
	v_mfma_f32_16x16x32_bf16 v[98:101], v[148:151], v[196:199], v[98:101]
	v_mfma_f32_16x16x32_bf16 v[94:97], v[166:169], v[196:199], v[94:97]
	v_mfma_f32_16x16x32_bf16 v[82:85], v[148:151], v[204:207], v[82:85]
	v_mfma_f32_16x16x32_bf16 v[78:81], v[166:169], v[204:207], v[78:81]
	s_barrier
	s_add_i32 s40, 0, 0x14000
	v_add_u32_e32 v140, s40, v142
	s_add_i32 s37, s37, s21
	ds_read_b128 v[208:211], v140
	ds_read_b128 v[212:215], v140 offset:1024
	ds_read_b128 v[216:219], v140 offset:2048
	ds_read_b128 v[220:223], v140 offset:3072
	v_lshl_add_u64 v[140:141], s[14:15], 0, v[134:135]
	s_mov_b32 m0, s37
	v_lshl_add_u64 v[154:155], s[14:15], 0, v[18:19]
	global_load_lds_dwordx4 v[140:141], off
	s_add_i32 m0, s37, 0x2000
	s_nop 0
	global_load_lds_dwordx4 v[154:155], off
	s_barrier
	s_waitcnt lgkmcnt(0)
	s_waitcnt lgkmcnt(0)
	v_mfma_f32_16x16x32_bf16 v[122:125], v[208:211], v[170:173], v[122:125]
	v_mfma_f32_16x16x32_bf16 v[118:121], v[216:219], v[170:173], v[118:121]
	v_mfma_f32_16x16x32_bf16 v[106:109], v[208:211], v[178:181], v[106:109]
	v_mfma_f32_16x16x32_bf16 v[102:105], v[216:219], v[178:181], v[102:105]
	v_mfma_f32_16x16x32_bf16 v[90:93], v[208:211], v[192:195], v[90:93]
	v_mfma_f32_16x16x32_bf16 v[86:89], v[216:219], v[192:195], v[86:89]
	v_mfma_f32_16x16x32_bf16 v[74:77], v[208:211], v[200:203], v[74:77]
	v_mfma_f32_16x16x32_bf16 v[70:73], v[216:219], v[200:203], v[70:73]
	v_mfma_f32_16x16x32_bf16 v[122:125], v[212:215], v[174:177], v[122:125]
	v_mfma_f32_16x16x32_bf16 v[118:121], v[220:223], v[174:177], v[118:121]
	v_mfma_f32_16x16x32_bf16 v[106:109], v[212:215], v[188:191], v[106:109]
	v_mfma_f32_16x16x32_bf16 v[102:105], v[220:223], v[188:191], v[102:105]
	v_mfma_f32_16x16x32_bf16 v[90:93], v[212:215], v[196:199], v[90:93]
	v_mfma_f32_16x16x32_bf16 v[86:89], v[220:223], v[196:199], v[86:89]
	v_mfma_f32_16x16x32_bf16 v[74:77], v[212:215], v[204:207], v[74:77]
	v_mfma_f32_16x16x32_bf16 v[70:73], v[220:223], v[204:207], v[70:73]
	s_mov_b32 m0, s23
	v_lshl_add_u64 v[156:157], s[16:17], 0, v[134:135]
	s_barrier
	ds_read_b128 v[170:173], v143 offset:16384
	ds_read_b128 v[174:177], v143 offset:17408
	ds_read_b128 v[178:181], v143 offset:18432
	ds_read_b128 v[188:191], v143 offset:19456
	ds_read_b128 v[192:195], v143 offset:20480
	ds_read_b128 v[196:199], v143 offset:21504
	ds_read_b128 v[200:203], v143 offset:22528
	ds_read_b128 v[204:207], v143 offset:23552
	global_load_lds_dwordx4 v[156:157], off
	v_lshl_add_u64 v[186:187], s[16:17], 0, v[18:19]
	s_mov_b32 m0, s24
	s_nop 0
	global_load_lds_dwordx4 v[186:187], off
	s_barrier
	s_waitcnt lgkmcnt(0)
	s_waitcnt lgkmcnt(0)
	v_mfma_f32_16x16x32_bf16 v[66:69], v[144:147], v[170:173], v[66:69]
	v_mfma_f32_16x16x32_bf16 v[62:65], v[162:165], v[170:173], v[62:65]
	v_mfma_f32_16x16x32_bf16 v[50:53], v[144:147], v[178:181], v[50:53]
	v_mfma_f32_16x16x32_bf16 v[46:49], v[162:165], v[178:181], v[46:49]
	v_mfma_f32_16x16x32_bf16 v[34:37], v[144:147], v[192:195], v[34:37]
	v_mfma_f32_16x16x32_bf16 v[30:33], v[162:165], v[192:195], v[30:33]
	v_mfma_f32_16x16x32_bf16 v[12:15], v[144:147], v[200:203], v[12:15]
	v_mfma_f32_16x16x32_bf16 v[8:11], v[162:165], v[200:203], v[8:11]
	v_mfma_f32_16x16x32_bf16 v[66:69], v[148:151], v[174:177], v[66:69]
	v_mfma_f32_16x16x32_bf16 v[62:65], v[166:169], v[174:177], v[62:65]
	v_mfma_f32_16x16x32_bf16 v[50:53], v[148:151], v[188:191], v[50:53]
	v_mfma_f32_16x16x32_bf16 v[46:49], v[166:169], v[188:191], v[46:49]
	v_mfma_f32_16x16x32_bf16 v[34:37], v[148:151], v[196:199], v[34:37]
	v_mfma_f32_16x16x32_bf16 v[30:33], v[166:169], v[196:199], v[30:33]
	v_mfma_f32_16x16x32_bf16 v[12:15], v[148:151], v[204:207], v[12:15]
	v_mfma_f32_16x16x32_bf16 v[8:11], v[166:169], v[204:207], v[8:11]
	s_barrier
; #define PG8_STAGE(bufoff, gbase, voff) do { _Pragma("unroll") for (int _i = 0; _i < 2; ++_i) \
;         __builtin_amdgcn_global_load_lds((const unsigned*)((const char*)(gbase) + (voff)[_i]), (PG8_LAS unsigned*)(lds + (bufoff) + ldsw + _i * 8192), 16, 0, 0); } while (0)
; #define PG8_LDA(dst, b, h) do { _Pragma("unroll") for (int m = 0; m < 4; ++m) _Pragma("unroll") for (int k = 0; k < 2; ++k) dst[m][k] = *(const PG8_LAS bf16x8*)(lds + PG8_SA(b, h) + aoff + m * 2048 + k * 1024); } while (0)
; #define PG8_LDB(dst, b, h) do { _Pragma("unroll") for (int n = 0; n < 2; ++n) _Pragma("unroll") for (int k = 0; k < 2; ++k) dst[n][k] = *(const PG8_LAS bf16x8*)(lds + PG8_SB(b, h) + boff + n * 2048 + k * 1024); } while (0)
; #define PG8_MMA(ai, bj, At, Bt) do { __builtin_amdgcn_s_setprio(1); _Pragma("unroll") for (int m = 0; m < 4; ++m) _Pragma("unroll") for (int n = 0; n < 2; ++n) _Pragma("unroll") for (int k = 0; k < 2; ++k) \
;         acc[ai][bj][m][n] = __builtin_amdgcn_mfma_f32_16x16x32_bf16(Bt[n][k], At[m][k], acc[ai][bj][m][n], 0, 0, 0); __builtin_amdgcn_s_setprio(0); } while (0)
; #define PG8_WAIT_V(n) asm volatile("s_waitcnt vmcnt(" #n ")" ::: "memory")
; #define PG8_WAIT_L(n) asm volatile("s_waitcnt lgkmcnt(" #n ")" ::: "memory")
; #define PG8_BAR __builtin_amdgcn_s_barrier()
; #define PG8_SCHED __builtin_amdgcn_sched_barrier(0)
; template <class Epi, class Sched>
; __device__ __forceinline__ void gemm_phase(PG8_LAS unsigned char* lds, const Gemm g, const Sched& S, const Epi& E) {
;     ...
;             PG8_STAGE(PG8_SB(0, 1), b2 + hstep, voffB);
;             PG8_WAIT_V(6); PG8_BAR; PG8_MMA(1, 1, At, B1); PG8_BAR;
;             PG8_LDB(B0, 1, 0); PG8_SCHED; PG8_LDA(At, 1, 0); PG8_STAGE(PG8_SA(0, 1), a2 + hstep, voffA);
;             PG8_WAIT_L(8); PG8_BAR; PG8_WAIT_L(0); PG8_MMA(0, 0, At, B0); PG8_BAR; PG8_SCHED;
;             PG8_LDB(B1, 1, 1); PG8_STAGE(PG8_SB(1, 0), b3, voffB);
;             PG8_BAR; PG8_WAIT_L(0); PG8_MMA(0, 1, At, B1); PG8_BAR;
;             PG8_LDA(At, 1, 1); PG8_STAGE(PG8_SA(1, 0), a3, voffA);
;             PG8_BAR; PG8_WAIT_L(0); PG8_MMA(1, 0, At, B0); PG8_BAR; PG8_SCHED;
;             PG8_STAGE(PG8_SB(1, 1), b3 + hstep, voffB);
;             PG8_WAIT_V(6); PG8_BAR; PG8_MMA(1, 1, At, B1); PG8_BAR;
	s_add_u32 s38, s14, 0x40000
	s_addc_u32 s39, s15, 0
	s_add_i32 s37, s40, s21
	v_lshl_add_u64 v[144:145], s[38:39], 0, v[134:135]
	s_mov_b32 m0, s37
	s_nop 0
	global_load_lds_dwordx4 v[144:145], off
	v_lshl_add_u64 v[144:145], s[38:39], 0, v[18:19]
	s_add_i32 m0, s37, 0x2000
	s_nop 0
	global_load_lds_dwordx4 v[144:145], off
	s_waitcnt vmcnt(6)
	s_barrier
	v_mfma_f32_16x16x32_bf16 v[58:61], v[208:211], v[170:173], v[58:61]
	v_mfma_f32_16x16x32_bf16 v[54:57], v[216:219], v[170:173], v[54:57]
	v_mfma_f32_16x16x32_bf16 v[42:45], v[208:211], v[178:181], v[42:45]
	v_mfma_f32_16x16x32_bf16 v[38:41], v[216:219], v[178:181], v[38:41]
	v_mfma_f32_16x16x32_bf16 v[26:29], v[208:211], v[192:195], v[26:29]
	v_mfma_f32_16x16x32_bf16 v[22:25], v[216:219], v[192:195], v[22:25]
	v_mfma_f32_16x16x32_bf16 v[4:7], v[208:211], v[200:203], v[4:7]
	v_mfma_f32_16x16x32_bf16 v[0:3], v[216:219], v[200:203], v[0:3]
	v_mfma_f32_16x16x32_bf16 v[58:61], v[212:215], v[174:177], v[58:61]
	v_mfma_f32_16x16x32_bf16 v[54:57], v[220:223], v[174:177], v[54:57]
	v_mfma_f32_16x16x32_bf16 v[42:45], v[212:215], v[188:191], v[42:45]
	v_mfma_f32_16x16x32_bf16 v[38:41], v[220:223], v[188:191], v[38:41]
	v_mfma_f32_16x16x32_bf16 v[26:29], v[212:215], v[196:199], v[26:29]
	v_mfma_f32_16x16x32_bf16 v[22:25], v[220:223], v[196:199], v[22:25]
	v_mfma_f32_16x16x32_bf16 v[4:7], v[212:215], v[204:207], v[4:7]
	v_mfma_f32_16x16x32_bf16 v[0:3], v[220:223], v[204:207], v[0:3]
	s_add_i32 s37, 0, 0x18000
	v_add_u32_e32 v166, s37, v142
	s_barrier
	ds_read_b128 v[144:147], v166
	ds_read_b128 v[148:151], v166 offset:1024
	ds_read_b128 v[162:165], v166 offset:2048
	ds_read_b128 v[166:169], v166 offset:3072
	s_add_u32 s16, s16, 0x40000
	s_addc_u32 s17, s17, 0
	s_mov_b32 m0, s25
	v_lshl_add_u64 v[208:209], s[16:17], 0, v[134:135]
	ds_read_b128 v[170:173], v143 offset:32768
	ds_read_b128 v[174:177], v143 offset:33792
	ds_read_b128 v[178:181], v143 offset:34816
	ds_read_b128 v[188:191], v143 offset:35840
	ds_read_b128 v[192:195], v143 offset:36864
	ds_read_b128 v[196:199], v143 offset:37888
	ds_read_b128 v[200:203], v143 offset:38912
	ds_read_b128 v[204:207], v143 offset:39936
	global_load_lds_dwordx4 v[208:209], off
	v_lshl_add_u64 v[208:209], s[16:17], 0, v[18:19]
	s_mov_b32 m0, s26
	s_nop 0
	global_load_lds_dwordx4 v[208:209], off
	s_waitcnt lgkmcnt(8)
	s_barrier
	s_waitcnt lgkmcnt(0)
	s_waitcnt lgkmcnt(0)
	v_mfma_f32_16x16x32_bf16 v[130:133], v[144:147], v[170:173], v[130:133]
	v_mfma_f32_16x16x32_bf16 v[126:129], v[162:165], v[170:173], v[126:129]
	v_mfma_f32_16x16x32_bf16 v[114:117], v[144:147], v[178:181], v[114:117]
	v_mfma_f32_16x16x32_bf16 v[110:113], v[162:165], v[178:181], v[110:113]
	v_mfma_f32_16x16x32_bf16 v[98:101], v[144:147], v[192:195], v[98:101]
	v_mfma_f32_16x16x32_bf16 v[94:97], v[162:165], v[192:195], v[94:97]
	v_mfma_f32_16x16x32_bf16 v[82:85], v[144:147], v[200:203], v[82:85]
	v_mfma_f32_16x16x32_bf16 v[78:81], v[162:165], v[200:203], v[78:81]
	v_mfma_f32_16x16x32_bf16 v[130:133], v[148:151], v[174:177], v[130:133]
	v_mfma_f32_16x16x32_bf16 v[126:129], v[166:169], v[174:177], v[126:129]
	v_mfma_f32_16x16x32_bf16 v[114:117], v[148:151], v[188:191], v[114:117]
	v_mfma_f32_16x16x32_bf16 v[110:113], v[166:169], v[188:191], v[110:113]
	v_mfma_f32_16x16x32_bf16 v[98:101], v[148:151], v[196:199], v[98:101]
	v_mfma_f32_16x16x32_bf16 v[94:97], v[166:169], v[196:199], v[94:97]
	v_mfma_f32_16x16x32_bf16 v[82:85], v[148:151], v[204:207], v[82:85]
	v_mfma_f32_16x16x32_bf16 v[78:81], v[166:169], v[204:207], v[78:81]
	s_barrier
	s_add_i32 s16, 0, 0x1c000
	s_add_i32 s17, s37, s21
	v_add_u32_e32 v220, s16, v142
	v_lshl_add_u64 v[140:141], v[140:141], 0, s[42:43]
	s_mov_b32 m0, s17
	ds_read_b128 v[208:211], v220
	ds_read_b128 v[212:215], v220 offset:1024
	ds_read_b128 v[216:219], v220 offset:2048
	ds_read_b128 v[220:223], v220 offset:3072
	global_load_lds_dwordx4 v[140:141], off
	v_lshl_add_u64 v[140:141], v[154:155], 0, s[42:43]
	s_add_i32 m0, s17, 0x2000
	s_nop 0
	global_load_lds_dwordx4 v[140:141], off
	s_barrier
	s_waitcnt lgkmcnt(0)
	s_waitcnt lgkmcnt(0)
	v_mfma_f32_16x16x32_bf16 v[122:125], v[208:211], v[170:173], v[122:125]
	v_mfma_f32_16x16x32_bf16 v[118:121], v[216:219], v[170:173], v[118:121]
	v_mfma_f32_16x16x32_bf16 v[106:109], v[208:211], v[178:181], v[106:109]
	v_mfma_f32_16x16x32_bf16 v[102:105], v[216:219], v[178:181], v[102:105]
	v_mfma_f32_16x16x32_bf16 v[90:93], v[208:211], v[192:195], v[90:93]
	v_mfma_f32_16x16x32_bf16 v[86:89], v[216:219], v[192:195], v[86:89]
	v_mfma_f32_16x16x32_bf16 v[74:77], v[208:211], v[200:203], v[74:77]
	v_mfma_f32_16x16x32_bf16 v[70:73], v[216:219], v[200:203], v[70:73]
	v_mfma_f32_16x16x32_bf16 v[122:125], v[212:215], v[174:177], v[122:125]
	v_mfma_f32_16x16x32_bf16 v[118:121], v[220:223], v[174:177], v[118:121]
	v_mfma_f32_16x16x32_bf16 v[106:109], v[212:215], v[188:191], v[106:109]
	v_mfma_f32_16x16x32_bf16 v[102:105], v[220:223], v[188:191], v[102:105]
	v_mfma_f32_16x16x32_bf16 v[90:93], v[212:215], v[196:199], v[90:93]
	v_mfma_f32_16x16x32_bf16 v[86:89], v[220:223], v[196:199], v[86:89]
	v_mfma_f32_16x16x32_bf16 v[74:77], v[212:215], v[204:207], v[74:77]
	v_mfma_f32_16x16x32_bf16 v[70:73], v[220:223], v[204:207], v[70:73]
	s_mov_b32 m0, s27
	v_lshl_add_u64 v[140:141], v[156:157], 0, s[42:43]
	s_barrier
	ds_read_b128 v[170:173], v143 offset:49152
	ds_read_b128 v[174:177], v143 offset:50176
	ds_read_b128 v[178:181], v143 offset:51200
	ds_read_b128 v[188:191], v143 offset:52224
	ds_read_b128 v[192:195], v143 offset:53248
	ds_read_b128 v[196:199], v143 offset:54272
	ds_read_b128 v[200:203], v143 offset:55296
	ds_read_b128 v[204:207], v143 offset:56320
	global_load_lds_dwordx4 v[140:141], off
	v_lshl_add_u64 v[140:141], v[186:187], 0, s[42:43]
	s_mov_b32 m0, s28
	s_nop 0
	global_load_lds_dwordx4 v[140:141], off
	s_barrier
; DI bf16x4 pack4(float a, float b, float c, float d) { u32x2v u; u.x = pk2(a, b); u.y = pk2(c, d); return __builtin_bit_cast(bf16x4, u); }
; #define PG8_WAIT_V(n) asm volatile("s_waitcnt vmcnt(" #n ")" ::: "memory")
; #define PG8_WAIT_L(n) asm volatile("s_waitcnt lgkmcnt(" #n ")" ::: "memory")
; #define PG8_BAR __builtin_amdgcn_s_barrier()
; template <class Epi, class Sched>
; __device__ __forceinline__ void gemm_phase(PG8_LAS unsigned char* lds, const Gemm g, const Sched& S, const Epi& E) {
;     ...
;             PG8_WAIT_V(6); PG8_BAR; PG8_MMA(1, 1, At, B1); PG8_BAR;
;             PG8_LDB(B0, 1, 0); PG8_SCHED; PG8_LDA(At, 1, 0); PG8_STAGE(PG8_SA(0, 1), a2 + hstep, voffA);
;             PG8_WAIT_L(8); PG8_BAR; PG8_WAIT_L(0); PG8_MMA(0, 0, At, B0); PG8_BAR; PG8_SCHED;
;             PG8_LDB(B1, 1, 1); PG8_STAGE(PG8_SB(1, 0), b3, voffB);
;             PG8_BAR; PG8_WAIT_L(0); PG8_MMA(0, 1, At, B1); PG8_BAR;
;             PG8_LDA(At, 1, 1); PG8_STAGE(PG8_SA(1, 0), a3, voffA);
;             PG8_BAR; PG8_WAIT_L(0); PG8_MMA(1, 0, At, B0); PG8_BAR; PG8_SCHED;
;             PG8_STAGE(PG8_SB(1, 1), b3 + hstep, voffB);
;             PG8_WAIT_V(6); PG8_BAR; PG8_MMA(1, 1, At, B1); PG8_BAR;
;   DI void operator()(const f32x4 (&acc)[2][2][4][2], const pg8::Unit& u, int wr, int wc, int fr, int fq) const {
;     bf16_t* MERGED = (reinterpret_cast<bf16_t*>(p.ws + OFF_GA));
; #pragma unroll
;     for (int ai = 0; ai < 2; ++ai)
; #pragma unroll
;       for (int m = 0; m < 4; ++m) {
;         const int row = u.pm * 256 + 128 * ai + 64 * wr + 16 * m + fr;
; #pragma unroll
;         for (int bj = 0; bj < 2; ++bj)
; #pragma unroll
;           for (int n = 0; n < 2; ++n) {
;             const size_t idx = (size_t)row * 1024 + u.pn * 256 + 128 * bj + 32 * wc + 16 * n + 4 * fq;
;             const f32x4 a = acc[ai][bj][m][n];
;             if (MODE == 0) {
;               const unsigned g = *reinterpret_cast<const unsigned*>(reinterpret_cast<const unsigned char*>(p.ws + OFF_RB) + idx);
;               const float k = 1.f / 255.f;
;               st4(MERGED + idx, pack4((float)(g & 255u) * k * a[0], (float)((g >> 8) & 255u) * k * a[1], (float)((g >> 16) & 255u) * k * a[2], (float)(g >> 24) * k * a[3]));
;             } else {
;               f32x4 x = *reinterpret_cast<const f32x4*>(p.out + idx);
;               x = x * ALPHA + a;
;               *reinterpret_cast<f32x4*>(p.out + idx) = x;
	s_waitcnt lgkmcnt(0)
	s_waitcnt lgkmcnt(0)
	v_mfma_f32_16x16x32_bf16 v[66:69], v[144:147], v[170:173], v[66:69]
	v_mfma_f32_16x16x32_bf16 v[62:65], v[162:165], v[170:173], v[62:65]
	v_mfma_f32_16x16x32_bf16 v[50:53], v[144:147], v[178:181], v[50:53]
	v_mfma_f32_16x16x32_bf16 v[46:49], v[162:165], v[178:181], v[46:49]
	v_mfma_f32_16x16x32_bf16 v[34:37], v[144:147], v[192:195], v[34:37]
	v_mfma_f32_16x16x32_bf16 v[30:33], v[162:165], v[192:195], v[30:33]
	v_mfma_f32_16x16x32_bf16 v[12:15], v[144:147], v[200:203], v[12:15]
	v_mfma_f32_16x16x32_bf16 v[8:11], v[162:165], v[200:203], v[8:11]
	v_mfma_f32_16x16x32_bf16 v[66:69], v[148:151], v[174:177], v[66:69]
	v_mfma_f32_16x16x32_bf16 v[62:65], v[166:169], v[174:177], v[62:65]
	v_mfma_f32_16x16x32_bf16 v[50:53], v[148:151], v[188:191], v[50:53]
	v_mfma_f32_16x16x32_bf16 v[46:49], v[166:169], v[188:191], v[46:49]
	v_mfma_f32_16x16x32_bf16 v[34:37], v[148:151], v[196:199], v[34:37]
	v_mfma_f32_16x16x32_bf16 v[30:33], v[166:169], v[196:199], v[30:33]
	v_mfma_f32_16x16x32_bf16 v[12:15], v[148:151], v[204:207], v[12:15]
	v_mfma_f32_16x16x32_bf16 v[8:11], v[166:169], v[204:207], v[8:11]
	s_barrier
	s_add_u32 s14, s14, 0x40080
	s_addc_u32 s15, s15, 0
	s_add_i32 s16, s16, s21
	v_lshl_add_u64 v[140:141], s[14:15], 0, v[134:135]
	s_mov_b32 m0, s16
	s_nop 0
	global_load_lds_dwordx4 v[140:141], off
	v_lshl_add_u64 v[140:141], s[14:15], 0, v[18:19]
	s_add_i32 m0, s16, 0x2000
	s_nop 0
	global_load_lds_dwordx4 v[140:141], off
	s_waitcnt vmcnt(6)
	s_barrier
	v_mfma_f32_16x16x32_bf16 v[58:61], v[208:211], v[170:173], v[58:61]
	v_mfma_f32_16x16x32_bf16 v[54:57], v[216:219], v[170:173], v[54:57]
	v_mfma_f32_16x16x32_bf16 v[42:45], v[208:211], v[178:181], v[42:45]
	v_mfma_f32_16x16x32_bf16 v[38:41], v[216:219], v[178:181], v[38:41]
	v_mfma_f32_16x16x32_bf16 v[26:29], v[208:211], v[192:195], v[26:29]
	v_mfma_f32_16x16x32_bf16 v[22:25], v[216:219], v[192:195], v[22:25]
	v_mfma_f32_16x16x32_bf16 v[4:7], v[208:211], v[200:203], v[4:7]
	v_mfma_f32_16x16x32_bf16 v[0:3], v[216:219], v[200:203], v[0:3]
	v_mfma_f32_16x16x32_bf16 v[58:61], v[212:215], v[174:177], v[58:61]
	v_mfma_f32_16x16x32_bf16 v[54:57], v[220:223], v[174:177], v[54:57]
	v_mfma_f32_16x16x32_bf16 v[42:45], v[212:215], v[188:191], v[42:45]
	v_mfma_f32_16x16x32_bf16 v[38:41], v[220:223], v[188:191], v[38:41]
	v_mfma_f32_16x16x32_bf16 v[26:29], v[212:215], v[196:199], v[26:29]
	v_mfma_f32_16x16x32_bf16 v[22:25], v[220:223], v[196:199], v[22:25]
	v_mfma_f32_16x16x32_bf16 v[4:7], v[212:215], v[204:207], v[4:7]
	v_mfma_f32_16x16x32_bf16 v[0:3], v[220:223], v[204:207], v[0:3]
	s_add_i32 s36, s36, 2
	s_add_u32 s12, s12, 0x100
	s_addc_u32 s13, s13, 0
	s_add_u32 s34, s34, 0x100
	s_addc_u32 s35, s35, 0
	s_cmp_gt_u32 s36, 13
	s_barrier
	s_cbranch_scc0 .LBB0_2754
	v_readlane_b32 s12, v251, 8
	s_cmp_eq_u32 s12, 0
	s_cbranch_scc1 .Llz_plain
	v_lshl_add_u32 v140, s10, 8, v21
	s_lshl_b32 s10, s11, 10
	v_readlane_b32 s14, v249, 4
	v_readlane_b32 s15, v249, 5
	v_readlane_b32 s13, v251, 6
	s_mov_b32 s16, 0x3fd744fd
	v_and_b32_e32 v147, 63, v153
	v_and_b32_e32 v148, 15, v153
	v_lshrrev_b32_e32 v149, 3, v147
	s_add_i32 s10, s10, s13
	s_add_i32 s12, s12, -1
	s_lshl_b32 s12, s12, 12
	v_sub_u32_e32 v140, v140, v148
	v_add_u32_e32 v140, v140, v149
	v_and_b32_e32 v146, 7, v153
	v_lshlrev_b32_e32 v141, 3, v140
	v_lshl_add_u32 v146, v146, 4, s10
	v_lshl_add_u32 v140, v140, 12, v146
	v_lshrrev_b32_e32 v144, 6, v153
	v_lshlrev_b32_e32 v144, 11, v144
	v_add_u32_e32 v144, 0x20000, v144
	v_lshl_add_u32 v145, v149, 6, v144
	v_lshl_add_u32 v144, v148, 6, v144
	v_bfe_u32 v148, v153, 4, 2
	v_lshl_add_u32 v144, v148, 4, v144
	v_bfe_u32 v148, v153, 2, 1
	v_lshl_add_u32 v145, v148, 10, v145
	v_and_b32_e32 v148, 3, v153
	v_lshl_add_u32 v145, v148, 4, v145
	v_readlane_b32 s72, v249, 38
	v_readlane_b32 s73, v249, 39
	v_readlane_b32 s74, v249, 40
	v_readlane_b32 s75, v249, 41
	v_readlane_b32 s76, v249, 0
	v_readlane_b32 s77, v249, 1
	s_add_u32 s72, s72, s12
	s_addc_u32 s73, s73, 0
	s_add_u32 s74, s74, s12
	s_addc_u32 s75, s75, 0
	s_add_u32 s76, s76, 0x2b234000
	s_addc_u32 s77, s77, 0
	s_add_u32 s56, s14, 0x0
	s_addc_u32 s57, s15, 0
	s_add_u32 s78, s14, 0x8000
	s_addc_u32 s79, s15, 0
	s_add_u32 s58, s14, 0x10000
	s_addc_u32 s59, s15, 0
	s_add_u32 s80, s14, 0x18000
	s_addc_u32 s81, s15, 0
	s_add_u32 s60, s14, 0x20000
	s_addc_u32 s61, s15, 0
	s_add_u32 s82, s14, 0x28000
	s_addc_u32 s83, s15, 0
	s_add_u32 s62, s14, 0x30000
	s_addc_u32 s63, s15, 0
	s_add_u32 s84, s14, 0x38000
	s_addc_u32 s85, s15, 0
	s_add_u32 s64, s14, 0x80000
	s_addc_u32 s65, s15, 0
	s_add_u32 s86, s14, 0x88000
	s_addc_u32 s87, s15, 0
	s_add_u32 s66, s14, 0x90000
	s_addc_u32 s67, s15, 0
	s_add_u32 s88, s14, 0x98000
	s_addc_u32 s89, s15, 0
	s_add_u32 s68, s14, 0xa0000
	s_addc_u32 s69, s15, 0
	s_add_u32 s90, s14, 0xa8000
	s_addc_u32 s91, s15, 0
	s_add_u32 s70, s14, 0xb0000
	s_addc_u32 s71, s15, 0
	s_add_u32 s92, s14, 0xb8000
	s_addc_u32 s93, s15, 0
	s_nop 1
	global_load_dwordx2 v[174:175], v141, s[76:77] offset:0
	global_load_dwordx2 v[176:177], v141, s[76:77] offset:64
	global_load_dwordx2 v[178:179], v141, s[76:77] offset:128
	global_load_dwordx2 v[180:181], v141, s[76:77] offset:192
	global_load_dwordx4 v[154:157], v146, s[72:73]
	global_load_dwordx4 v[162:165], v146, s[74:75]
	global_load_dwordx4 v[166:169], v146, s[72:73] offset:512
	global_load_dwordx4 v[170:173], v146, s[74:75] offset:512
	global_load_dwordx4 v[204:207], v140, s[56:57]
	global_load_dwordx4 v[208:211], v140, s[78:79]
	global_load_dwordx4 v[212:215], v140, s[56:57] offset:512
	global_load_dwordx4 v[216:219], v140, s[78:79] offset:512
	global_load_dwordx4 v[220:223], v140, s[58:59]
	global_load_dwordx4 v[224:227], v140, s[80:81]
	global_load_dwordx4 v[228:231], v140, s[58:59] offset:512
	global_load_dwordx4 v[232:235], v140, s[80:81] offset:512
	global_load_dwordx4 v[236:239], v140, s[60:61]
	global_load_dwordx4 v[240:243], v140, s[82:83]
	global_load_dwordx4 v[244:247], v140, s[60:61] offset:512
	ds_write_b128 v144, v[130:133]
	ds_write_b128 v144, v[126:129] offset:1024
	ds_read_b128 v[186:189], v145
	ds_read_b128 v[190:193], v145 offset:512
	ds_write_b128 v144, v[122:125]
	ds_write_b128 v144, v[118:121] offset:1024
	ds_read_b128 v[194:197], v145
	ds_read_b128 v[198:201], v145 offset:512
	s_waitcnt lgkmcnt(4)
; DI void ln_row_wave(const float* src, const float* g, const float* b, float* d32, bf16_t* db, int lane) {
;     ...
;     o.x = (v[i].x - mu) * rstd * gg.x + bb.x; o.y = (v[i].y - mu) * rstd * gg.y + bb.y;
;   DI void operator()(const f32x4 (&acc)[2][2][4][2], const pg8::Unit& u, int wr, int wc, int fr, int fq) const {
;     ...
;               f32x4 x = *reinterpret_cast<const f32x4*>(p.out + idx);
;               x = x * ALPHA + a;
;               *reinterpret_cast<f32x4*>(p.out + idx) = x;
	s_waitcnt vmcnt(10)
	v_pk_add_f32 v[204:205], v[204:205], v[174:175] op_sel_hi:[1,0] neg_lo:[0,1] neg_hi:[0,1]
	v_pk_add_f32 v[206:207], v[206:207], v[174:175] op_sel_hi:[1,0] neg_lo:[0,1] neg_hi:[0,1]
	v_pk_mul_f32 v[204:205], v[204:205], v[174:175] op_sel:[0,1] op_sel_hi:[1,1]
	v_pk_mul_f32 v[206:207], v[206:207], v[174:175] op_sel:[0,1] op_sel_hi:[1,1]
	v_pk_fma_f32 v[204:205], v[204:205], v[154:155], v[162:163]
	v_pk_fma_f32 v[206:207], v[206:207], v[156:157], v[164:165]
	v_pk_fma_f32 v[186:187], v[204:205], s[16:17], v[186:187] op_sel_hi:[1,0,1]
	v_pk_fma_f32 v[188:189], v[206:207], s[16:17], v[188:189] op_sel_hi:[1,0,1]
	global_store_dwordx4 v140, v[186:189], s[56:57]
	global_load_dwordx4 v[204:207], v140, s[82:83] offset:512
	s_waitcnt vmcnt(11)
	v_pk_add_f32 v[208:209], v[208:209], v[176:177] op_sel_hi:[1,0] neg_lo:[0,1] neg_hi:[0,1]
	v_pk_add_f32 v[210:211], v[210:211], v[176:177] op_sel_hi:[1,0] neg_lo:[0,1] neg_hi:[0,1]
	v_pk_mul_f32 v[208:209], v[208:209], v[176:177] op_sel:[0,1] op_sel_hi:[1,1]
	v_pk_mul_f32 v[210:211], v[210:211], v[176:177] op_sel:[0,1] op_sel_hi:[1,1]
	v_pk_fma_f32 v[208:209], v[208:209], v[154:155], v[162:163]
	v_pk_fma_f32 v[210:211], v[210:211], v[156:157], v[164:165]
	v_pk_fma_f32 v[190:191], v[208:209], s[16:17], v[190:191] op_sel_hi:[1,0,1]
	v_pk_fma_f32 v[192:193], v[210:211], s[16:17], v[192:193] op_sel_hi:[1,0,1]
	global_store_dwordx4 v140, v[190:193], s[78:79]
	global_load_dwordx4 v[208:211], v140, s[62:63]
	ds_write_b128 v144, v[114:117]
	ds_write_b128 v144, v[110:113] offset:1024
	ds_read_b128 v[186:189], v145
	ds_read_b128 v[190:193], v145 offset:512
	s_waitcnt lgkmcnt(4)
	s_waitcnt vmcnt(12)
	v_pk_add_f32 v[212:213], v[212:213], v[174:175] op_sel_hi:[1,0] neg_lo:[0,1] neg_hi:[0,1]
	v_pk_add_f32 v[214:215], v[214:215], v[174:175] op_sel_hi:[1,0] neg_lo:[0,1] neg_hi:[0,1]
	v_pk_mul_f32 v[212:213], v[212:213], v[174:175] op_sel:[0,1] op_sel_hi:[1,1]
	v_pk_mul_f32 v[214:215], v[214:215], v[174:175] op_sel:[0,1] op_sel_hi:[1,1]
	v_pk_fma_f32 v[212:213], v[212:213], v[166:167], v[170:171]
	v_pk_fma_f32 v[214:215], v[214:215], v[168:169], v[172:173]
	v_pk_fma_f32 v[194:195], v[212:213], s[16:17], v[194:195] op_sel_hi:[1,0,1]
	v_pk_fma_f32 v[196:197], v[214:215], s[16:17], v[196:197] op_sel_hi:[1,0,1]
	global_store_dwordx4 v140, v[194:197], s[56:57] offset:512
	global_load_dwordx4 v[212:215], v140, s[84:85]
	s_waitcnt vmcnt(13)
	v_pk_add_f32 v[216:217], v[216:217], v[176:177] op_sel_hi:[1,0] neg_lo:[0,1] neg_hi:[0,1]
	v_pk_add_f32 v[218:219], v[218:219], v[176:177] op_sel_hi:[1,0] neg_lo:[0,1] neg_hi:[0,1]
	v_pk_mul_f32 v[216:217], v[216:217], v[176:177] op_sel:[0,1] op_sel_hi:[1,1]
	v_pk_mul_f32 v[218:219], v[218:219], v[176:177] op_sel:[0,1] op_sel_hi:[1,1]
	v_pk_fma_f32 v[216:217], v[216:217], v[166:167], v[170:171]
	v_pk_fma_f32 v[218:219], v[218:219], v[168:169], v[172:173]
	v_pk_fma_f32 v[198:199], v[216:217], s[16:17], v[198:199] op_sel_hi:[1,0,1]
	v_pk_fma_f32 v[200:201], v[218:219], s[16:17], v[200:201] op_sel_hi:[1,0,1]
	global_store_dwordx4 v140, v[198:201], s[78:79] offset:512
	global_load_dwordx4 v[216:219], v140, s[62:63] offset:512
	global_load_dwordx2 v[174:175], v141, s[76:77] offset:256
	global_load_dwordx2 v[176:177], v141, s[76:77] offset:320
	ds_write_b128 v144, v[106:109]
	ds_write_b128 v144, v[102:105] offset:1024
	ds_read_b128 v[194:197], v145
	ds_read_b128 v[198:201], v145 offset:512
	s_waitcnt lgkmcnt(4)
	s_waitcnt vmcnt(16)
	v_pk_add_f32 v[220:221], v[220:221], v[178:179] op_sel_hi:[1,0] neg_lo:[0,1] neg_hi:[0,1]
	v_pk_add_f32 v[222:223], v[222:223], v[178:179] op_sel_hi:[1,0] neg_lo:[0,1] neg_hi:[0,1]
	v_pk_mul_f32 v[220:221], v[220:221], v[178:179] op_sel:[0,1] op_sel_hi:[1,1]
	v_pk_mul_f32 v[222:223], v[222:223], v[178:179] op_sel:[0,1] op_sel_hi:[1,1]
	v_pk_fma_f32 v[220:221], v[220:221], v[154:155], v[162:163]
	v_pk_fma_f32 v[222:223], v[222:223], v[156:157], v[164:165]
	v_pk_fma_f32 v[186:187], v[220:221], s[16:17], v[186:187] op_sel_hi:[1,0,1]
	v_pk_fma_f32 v[188:189], v[222:223], s[16:17], v[188:189] op_sel_hi:[1,0,1]
	global_store_dwordx4 v140, v[186:189], s[58:59]
	global_load_dwordx4 v[220:223], v140, s[84:85] offset:512
	s_waitcnt vmcnt(17)
	v_pk_add_f32 v[224:225], v[224:225], v[180:181] op_sel_hi:[1,0] neg_lo:[0,1] neg_hi:[0,1]
	v_pk_add_f32 v[226:227], v[226:227], v[180:181] op_sel_hi:[1,0] neg_lo:[0,1] neg_hi:[0,1]
	v_pk_mul_f32 v[224:225], v[224:225], v[180:181] op_sel:[0,1] op_sel_hi:[1,1]
	v_pk_mul_f32 v[226:227], v[226:227], v[180:181] op_sel:[0,1] op_sel_hi:[1,1]
	v_pk_fma_f32 v[224:225], v[224:225], v[154:155], v[162:163]
	v_pk_fma_f32 v[226:227], v[226:227], v[156:157], v[164:165]
	v_pk_fma_f32 v[190:191], v[224:225], s[16:17], v[190:191] op_sel_hi:[1,0,1]
	v_pk_fma_f32 v[192:193], v[226:227], s[16:17], v[192:193] op_sel_hi:[1,0,1]
	global_store_dwordx4 v140, v[190:193], s[80:81]
	global_load_dwordx4 v[224:227], v140, s[64:65]
	ds_write_b128 v144, v[98:101]
	ds_write_b128 v144, v[94:97] offset:1024
	ds_read_b128 v[186:189], v145
	ds_read_b128 v[190:193], v145 offset:512
	s_waitcnt lgkmcnt(4)
	s_waitcnt vmcnt(18)
	v_pk_add_f32 v[228:229], v[228:229], v[178:179] op_sel_hi:[1,0] neg_lo:[0,1] neg_hi:[0,1]
	v_pk_add_f32 v[230:231], v[230:231], v[178:179] op_sel_hi:[1,0] neg_lo:[0,1] neg_hi:[0,1]
	v_pk_mul_f32 v[228:229], v[228:229], v[178:179] op_sel:[0,1] op_sel_hi:[1,1]
	v_pk_mul_f32 v[230:231], v[230:231], v[178:179] op_sel:[0,1] op_sel_hi:[1,1]
	v_pk_fma_f32 v[228:229], v[228:229], v[166:167], v[170:171]
	v_pk_fma_f32 v[230:231], v[230:231], v[168:169], v[172:173]
	v_pk_fma_f32 v[194:195], v[228:229], s[16:17], v[194:195] op_sel_hi:[1,0,1]
	v_pk_fma_f32 v[196:197], v[230:231], s[16:17], v[196:197] op_sel_hi:[1,0,1]
	global_store_dwordx4 v140, v[194:197], s[58:59] offset:512
	global_load_dwordx4 v[228:231], v140, s[86:87]
	s_waitcnt vmcnt(19)
; DI void ln_row_wave(const float* src, const float* g, const float* b, float* d32, bf16_t* db, int lane) {
;     ...
;     o.x = (v[i].x - mu) * rstd * gg.x + bb.x; o.y = (v[i].y - mu) * rstd * gg.y + bb.y;
;   DI void operator()(const f32x4 (&acc)[2][2][4][2], const pg8::Unit& u, int wr, int wc, int fr, int fq) const {
;     ...
;               f32x4 x = *reinterpret_cast<const f32x4*>(p.out + idx);
;               x = x * ALPHA + a;
;               *reinterpret_cast<f32x4*>(p.out + idx) = x;
	v_pk_add_f32 v[232:233], v[232:233], v[180:181] op_sel_hi:[1,0] neg_lo:[0,1] neg_hi:[0,1]
	v_pk_add_f32 v[234:235], v[234:235], v[180:181] op_sel_hi:[1,0] neg_lo:[0,1] neg_hi:[0,1]
	v_pk_mul_f32 v[232:233], v[232:233], v[180:181] op_sel:[0,1] op_sel_hi:[1,1]
	v_pk_mul_f32 v[234:235], v[234:235], v[180:181] op_sel:[0,1] op_sel_hi:[1,1]
	v_pk_fma_f32 v[232:233], v[232:233], v[166:167], v[170:171]
	v_pk_fma_f32 v[234:235], v[234:235], v[168:169], v[172:173]
	v_pk_fma_f32 v[198:199], v[232:233], s[16:17], v[198:199] op_sel_hi:[1,0,1]
	v_pk_fma_f32 v[200:201], v[234:235], s[16:17], v[200:201] op_sel_hi:[1,0,1]
	global_store_dwordx4 v140, v[198:201], s[80:81] offset:512
	global_load_dwordx4 v[232:235], v140, s[64:65] offset:512
	global_load_dwordx2 v[178:179], v141, s[76:77] offset:384
	global_load_dwordx2 v[180:181], v141, s[76:77] offset:448
	ds_write_b128 v144, v[90:93]
	ds_write_b128 v144, v[86:89] offset:1024
	ds_read_b128 v[194:197], v145
	ds_read_b128 v[198:201], v145 offset:512
	s_waitcnt lgkmcnt(4)
	s_waitcnt vmcnt(11)
	v_pk_add_f32 v[236:237], v[236:237], v[174:175] op_sel_hi:[1,0] neg_lo:[0,1] neg_hi:[0,1]
	v_pk_add_f32 v[238:239], v[238:239], v[174:175] op_sel_hi:[1,0] neg_lo:[0,1] neg_hi:[0,1]
	v_pk_mul_f32 v[236:237], v[236:237], v[174:175] op_sel:[0,1] op_sel_hi:[1,1]
	v_pk_mul_f32 v[238:239], v[238:239], v[174:175] op_sel:[0,1] op_sel_hi:[1,1]
	v_pk_fma_f32 v[236:237], v[236:237], v[154:155], v[162:163]
	v_pk_fma_f32 v[238:239], v[238:239], v[156:157], v[164:165]
	v_pk_fma_f32 v[186:187], v[236:237], s[16:17], v[186:187] op_sel_hi:[1,0,1]
	v_pk_fma_f32 v[188:189], v[238:239], s[16:17], v[188:189] op_sel_hi:[1,0,1]
	global_store_dwordx4 v140, v[186:189], s[60:61]
	global_load_dwordx4 v[236:239], v140, s[86:87] offset:512
	s_waitcnt vmcnt(12)
	v_pk_add_f32 v[240:241], v[240:241], v[176:177] op_sel_hi:[1,0] neg_lo:[0,1] neg_hi:[0,1]
	v_pk_add_f32 v[242:243], v[242:243], v[176:177] op_sel_hi:[1,0] neg_lo:[0,1] neg_hi:[0,1]
	v_pk_mul_f32 v[240:241], v[240:241], v[176:177] op_sel:[0,1] op_sel_hi:[1,1]
	v_pk_mul_f32 v[242:243], v[242:243], v[176:177] op_sel:[0,1] op_sel_hi:[1,1]
	v_pk_fma_f32 v[240:241], v[240:241], v[154:155], v[162:163]
	v_pk_fma_f32 v[242:243], v[242:243], v[156:157], v[164:165]
	v_pk_fma_f32 v[190:191], v[240:241], s[16:17], v[190:191] op_sel_hi:[1,0,1]
	v_pk_fma_f32 v[192:193], v[242:243], s[16:17], v[192:193] op_sel_hi:[1,0,1]
	global_store_dwordx4 v140, v[190:193], s[82:83]
	global_load_dwordx4 v[240:243], v140, s[66:67]
	ds_write_b128 v144, v[82:85]
	ds_write_b128 v144, v[78:81] offset:1024
	ds_read_b128 v[186:189], v145
	ds_read_b128 v[190:193], v145 offset:512
	s_waitcnt lgkmcnt(4)
	s_waitcnt vmcnt(15)
	v_pk_add_f32 v[244:245], v[244:245], v[174:175] op_sel_hi:[1,0] neg_lo:[0,1] neg_hi:[0,1]
	v_pk_add_f32 v[246:247], v[246:247], v[174:175] op_sel_hi:[1,0] neg_lo:[0,1] neg_hi:[0,1]
	v_pk_mul_f32 v[244:245], v[244:245], v[174:175] op_sel:[0,1] op_sel_hi:[1,1]
	v_pk_mul_f32 v[246:247], v[246:247], v[174:175] op_sel:[0,1] op_sel_hi:[1,1]
	v_pk_fma_f32 v[244:245], v[244:245], v[166:167], v[170:171]
	v_pk_fma_f32 v[246:247], v[246:247], v[168:169], v[172:173]
	v_pk_fma_f32 v[194:195], v[244:245], s[16:17], v[194:195] op_sel_hi:[1,0,1]
	v_pk_fma_f32 v[196:197], v[246:247], s[16:17], v[196:197] op_sel_hi:[1,0,1]
	global_store_dwordx4 v140, v[194:197], s[60:61] offset:512
	global_load_dwordx4 v[244:247], v140, s[88:89]
	s_waitcnt vmcnt(16)
	v_pk_add_f32 v[204:205], v[204:205], v[176:177] op_sel_hi:[1,0] neg_lo:[0,1] neg_hi:[0,1]
	v_pk_add_f32 v[206:207], v[206:207], v[176:177] op_sel_hi:[1,0] neg_lo:[0,1] neg_hi:[0,1]
	v_pk_mul_f32 v[204:205], v[204:205], v[176:177] op_sel:[0,1] op_sel_hi:[1,1]
	v_pk_mul_f32 v[206:207], v[206:207], v[176:177] op_sel:[0,1] op_sel_hi:[1,1]
	v_pk_fma_f32 v[204:205], v[204:205], v[166:167], v[170:171]
	v_pk_fma_f32 v[206:207], v[206:207], v[168:169], v[172:173]
	v_pk_fma_f32 v[198:199], v[204:205], s[16:17], v[198:199] op_sel_hi:[1,0,1]
	v_pk_fma_f32 v[200:201], v[206:207], s[16:17], v[200:201] op_sel_hi:[1,0,1]
	global_store_dwordx4 v140, v[198:201], s[82:83] offset:512
	global_load_dwordx4 v[204:207], v140, s[66:67] offset:512
	global_load_dwordx2 v[174:175], v141, s[76:77] offset:1024
	global_load_dwordx2 v[176:177], v141, s[76:77] offset:1088
	ds_write_b128 v144, v[74:77]
	ds_write_b128 v144, v[70:73] offset:1024
	ds_read_b128 v[194:197], v145
	ds_read_b128 v[198:201], v145 offset:512
	s_waitcnt lgkmcnt(4)
	s_waitcnt vmcnt(11)
	v_pk_add_f32 v[208:209], v[208:209], v[178:179] op_sel_hi:[1,0] neg_lo:[0,1] neg_hi:[0,1]
	v_pk_add_f32 v[210:211], v[210:211], v[178:179] op_sel_hi:[1,0] neg_lo:[0,1] neg_hi:[0,1]
	v_pk_mul_f32 v[208:209], v[208:209], v[178:179] op_sel:[0,1] op_sel_hi:[1,1]
	v_pk_mul_f32 v[210:211], v[210:211], v[178:179] op_sel:[0,1] op_sel_hi:[1,1]
	v_pk_fma_f32 v[208:209], v[208:209], v[154:155], v[162:163]
	v_pk_fma_f32 v[210:211], v[210:211], v[156:157], v[164:165]
	v_pk_fma_f32 v[186:187], v[208:209], s[16:17], v[186:187] op_sel_hi:[1,0,1]
	v_pk_fma_f32 v[188:189], v[210:211], s[16:17], v[188:189] op_sel_hi:[1,0,1]
	global_store_dwordx4 v140, v[186:189], s[62:63]
	global_load_dwordx4 v[208:211], v140, s[88:89] offset:512
	s_waitcnt vmcnt(12)
; DI void ln_row_wave(const float* src, const float* g, const float* b, float* d32, bf16_t* db, int lane) {
;     ...
;     o.x = (v[i].x - mu) * rstd * gg.x + bb.x; o.y = (v[i].y - mu) * rstd * gg.y + bb.y;
;   DI void operator()(const f32x4 (&acc)[2][2][4][2], const pg8::Unit& u, int wr, int wc, int fr, int fq) const {
;     ...
;               f32x4 x = *reinterpret_cast<const f32x4*>(p.out + idx);
;               x = x * ALPHA + a;
;               *reinterpret_cast<f32x4*>(p.out + idx) = x;
	v_pk_add_f32 v[212:213], v[212:213], v[180:181] op_sel_hi:[1,0] neg_lo:[0,1] neg_hi:[0,1]
	v_pk_add_f32 v[214:215], v[214:215], v[180:181] op_sel_hi:[1,0] neg_lo:[0,1] neg_hi:[0,1]
	v_pk_mul_f32 v[212:213], v[212:213], v[180:181] op_sel:[0,1] op_sel_hi:[1,1]
	v_pk_mul_f32 v[214:215], v[214:215], v[180:181] op_sel:[0,1] op_sel_hi:[1,1]
	v_pk_fma_f32 v[212:213], v[212:213], v[154:155], v[162:163]
	v_pk_fma_f32 v[214:215], v[214:215], v[156:157], v[164:165]
	v_pk_fma_f32 v[190:191], v[212:213], s[16:17], v[190:191] op_sel_hi:[1,0,1]
	v_pk_fma_f32 v[192:193], v[214:215], s[16:17], v[192:193] op_sel_hi:[1,0,1]
	global_store_dwordx4 v140, v[190:193], s[84:85]
	global_load_dwordx4 v[212:215], v140, s[68:69]
	ds_write_b128 v144, v[66:69]
	ds_write_b128 v144, v[62:65] offset:1024
	ds_read_b128 v[186:189], v145
	ds_read_b128 v[190:193], v145 offset:512
	s_waitcnt lgkmcnt(4)
	s_waitcnt vmcnt(15)
	v_pk_add_f32 v[216:217], v[216:217], v[178:179] op_sel_hi:[1,0] neg_lo:[0,1] neg_hi:[0,1]
	v_pk_add_f32 v[218:219], v[218:219], v[178:179] op_sel_hi:[1,0] neg_lo:[0,1] neg_hi:[0,1]
	v_pk_mul_f32 v[216:217], v[216:217], v[178:179] op_sel:[0,1] op_sel_hi:[1,1]
	v_pk_mul_f32 v[218:219], v[218:219], v[178:179] op_sel:[0,1] op_sel_hi:[1,1]
	v_pk_fma_f32 v[216:217], v[216:217], v[166:167], v[170:171]
	v_pk_fma_f32 v[218:219], v[218:219], v[168:169], v[172:173]
	v_pk_fma_f32 v[194:195], v[216:217], s[16:17], v[194:195] op_sel_hi:[1,0,1]
	v_pk_fma_f32 v[196:197], v[218:219], s[16:17], v[196:197] op_sel_hi:[1,0,1]
	global_store_dwordx4 v140, v[194:197], s[62:63] offset:512
	global_load_dwordx4 v[216:219], v140, s[90:91]
	s_waitcnt vmcnt(16)
	v_pk_add_f32 v[220:221], v[220:221], v[180:181] op_sel_hi:[1,0] neg_lo:[0,1] neg_hi:[0,1]
	v_pk_add_f32 v[222:223], v[222:223], v[180:181] op_sel_hi:[1,0] neg_lo:[0,1] neg_hi:[0,1]
	v_pk_mul_f32 v[220:221], v[220:221], v[180:181] op_sel:[0,1] op_sel_hi:[1,1]
	v_pk_mul_f32 v[222:223], v[222:223], v[180:181] op_sel:[0,1] op_sel_hi:[1,1]
	v_pk_fma_f32 v[220:221], v[220:221], v[166:167], v[170:171]
	v_pk_fma_f32 v[222:223], v[222:223], v[168:169], v[172:173]
	v_pk_fma_f32 v[198:199], v[220:221], s[16:17], v[198:199] op_sel_hi:[1,0,1]
	v_pk_fma_f32 v[200:201], v[222:223], s[16:17], v[200:201] op_sel_hi:[1,0,1]
	global_store_dwordx4 v140, v[198:201], s[84:85] offset:512
	global_load_dwordx4 v[220:223], v140, s[68:69] offset:512
	global_load_dwordx2 v[178:179], v141, s[76:77] offset:1152
	global_load_dwordx2 v[180:181], v141, s[76:77] offset:1216
	ds_write_b128 v144, v[58:61]
	ds_write_b128 v144, v[54:57] offset:1024
	ds_read_b128 v[194:197], v145
	ds_read_b128 v[198:201], v145 offset:512
	s_waitcnt lgkmcnt(4)
	s_waitcnt vmcnt(11)
	v_pk_add_f32 v[224:225], v[224:225], v[174:175] op_sel_hi:[1,0] neg_lo:[0,1] neg_hi:[0,1]
	v_pk_add_f32 v[226:227], v[226:227], v[174:175] op_sel_hi:[1,0] neg_lo:[0,1] neg_hi:[0,1]
	v_pk_mul_f32 v[224:225], v[224:225], v[174:175] op_sel:[0,1] op_sel_hi:[1,1]
	v_pk_mul_f32 v[226:227], v[226:227], v[174:175] op_sel:[0,1] op_sel_hi:[1,1]
	v_pk_fma_f32 v[224:225], v[224:225], v[154:155], v[162:163]
	v_pk_fma_f32 v[226:227], v[226:227], v[156:157], v[164:165]
	v_pk_fma_f32 v[186:187], v[224:225], s[16:17], v[186:187] op_sel_hi:[1,0,1]
	v_pk_fma_f32 v[188:189], v[226:227], s[16:17], v[188:189] op_sel_hi:[1,0,1]
	global_store_dwordx4 v140, v[186:189], s[64:65]
	global_load_dwordx4 v[224:227], v140, s[90:91] offset:512
	s_waitcnt vmcnt(12)
	v_pk_add_f32 v[228:229], v[228:229], v[176:177] op_sel_hi:[1,0] neg_lo:[0,1] neg_hi:[0,1]
	v_pk_add_f32 v[230:231], v[230:231], v[176:177] op_sel_hi:[1,0] neg_lo:[0,1] neg_hi:[0,1]
	v_pk_mul_f32 v[228:229], v[228:229], v[176:177] op_sel:[0,1] op_sel_hi:[1,1]
	v_pk_mul_f32 v[230:231], v[230:231], v[176:177] op_sel:[0,1] op_sel_hi:[1,1]
	v_pk_fma_f32 v[228:229], v[228:229], v[154:155], v[162:163]
	v_pk_fma_f32 v[230:231], v[230:231], v[156:157], v[164:165]
	v_pk_fma_f32 v[190:191], v[228:229], s[16:17], v[190:191] op_sel_hi:[1,0,1]
	v_pk_fma_f32 v[192:193], v[230:231], s[16:17], v[192:193] op_sel_hi:[1,0,1]
	global_store_dwordx4 v140, v[190:193], s[86:87]
	global_load_dwordx4 v[228:231], v140, s[70:71]
	ds_write_b128 v144, v[50:53]
	ds_write_b128 v144, v[46:49] offset:1024
	ds_read_b128 v[186:189], v145
	ds_read_b128 v[190:193], v145 offset:512
	s_waitcnt lgkmcnt(4)
	s_waitcnt vmcnt(15)
	v_pk_add_f32 v[232:233], v[232:233], v[174:175] op_sel_hi:[1,0] neg_lo:[0,1] neg_hi:[0,1]
	v_pk_add_f32 v[234:235], v[234:235], v[174:175] op_sel_hi:[1,0] neg_lo:[0,1] neg_hi:[0,1]
	v_pk_mul_f32 v[232:233], v[232:233], v[174:175] op_sel:[0,1] op_sel_hi:[1,1]
	v_pk_mul_f32 v[234:235], v[234:235], v[174:175] op_sel:[0,1] op_sel_hi:[1,1]
	v_pk_fma_f32 v[232:233], v[232:233], v[166:167], v[170:171]
	v_pk_fma_f32 v[234:235], v[234:235], v[168:169], v[172:173]
	v_pk_fma_f32 v[194:195], v[232:233], s[16:17], v[194:195] op_sel_hi:[1,0,1]
	v_pk_fma_f32 v[196:197], v[234:235], s[16:17], v[196:197] op_sel_hi:[1,0,1]
	global_store_dwordx4 v140, v[194:197], s[64:65] offset:512
	global_load_dwordx4 v[232:235], v140, s[92:93]
	s_waitcnt vmcnt(16)
	v_pk_add_f32 v[236:237], v[236:237], v[176:177] op_sel_hi:[1,0] neg_lo:[0,1] neg_hi:[0,1]
	v_pk_add_f32 v[238:239], v[238:239], v[176:177] op_sel_hi:[1,0] neg_lo:[0,1] neg_hi:[0,1]
	v_pk_mul_f32 v[236:237], v[236:237], v[176:177] op_sel:[0,1] op_sel_hi:[1,1]
	v_pk_mul_f32 v[238:239], v[238:239], v[176:177] op_sel:[0,1] op_sel_hi:[1,1]
	v_pk_fma_f32 v[236:237], v[236:237], v[166:167], v[170:171]
	v_pk_fma_f32 v[238:239], v[238:239], v[168:169], v[172:173]
	v_pk_fma_f32 v[198:199], v[236:237], s[16:17], v[198:199] op_sel_hi:[1,0,1]
	v_pk_fma_f32 v[200:201], v[238:239], s[16:17], v[200:201] op_sel_hi:[1,0,1]
	global_store_dwordx4 v140, v[198:201], s[86:87] offset:512
	global_load_dwordx4 v[236:239], v140, s[70:71] offset:512
	global_load_dwordx2 v[174:175], v141, s[76:77] offset:1280
	global_load_dwordx2 v[176:177], v141, s[76:77] offset:1344
	ds_write_b128 v144, v[42:45]
	ds_write_b128 v144, v[38:41] offset:1024
	ds_read_b128 v[194:197], v145
	ds_read_b128 v[198:201], v145 offset:512
	s_waitcnt lgkmcnt(4)
; DI void ln_row_wave(const float* src, const float* g, const float* b, float* d32, bf16_t* db, int lane) {
;     ...
;     o.x = (v[i].x - mu) * rstd * gg.x + bb.x; o.y = (v[i].y - mu) * rstd * gg.y + bb.y;
;   DI void operator()(const f32x4 (&acc)[2][2][4][2], const pg8::Unit& u, int wr, int wc, int fr, int fq) const {
;     ...
;               f32x4 x = *reinterpret_cast<const f32x4*>(p.out + idx);
;               x = x * ALPHA + a;
;               *reinterpret_cast<f32x4*>(p.out + idx) = x;
	s_waitcnt vmcnt(11)
	v_pk_add_f32 v[240:241], v[240:241], v[178:179] op_sel_hi:[1,0] neg_lo:[0,1] neg_hi:[0,1]
	v_pk_add_f32 v[242:243], v[242:243], v[178:179] op_sel_hi:[1,0] neg_lo:[0,1] neg_hi:[0,1]
	v_pk_mul_f32 v[240:241], v[240:241], v[178:179] op_sel:[0,1] op_sel_hi:[1,1]
	v_pk_mul_f32 v[242:243], v[242:243], v[178:179] op_sel:[0,1] op_sel_hi:[1,1]
	v_pk_fma_f32 v[240:241], v[240:241], v[154:155], v[162:163]
	v_pk_fma_f32 v[242:243], v[242:243], v[156:157], v[164:165]
	v_pk_fma_f32 v[186:187], v[240:241], s[16:17], v[186:187] op_sel_hi:[1,0,1]
	v_pk_fma_f32 v[188:189], v[242:243], s[16:17], v[188:189] op_sel_hi:[1,0,1]
	global_store_dwordx4 v140, v[186:189], s[66:67]
	global_load_dwordx4 v[240:243], v140, s[92:93] offset:512
	s_waitcnt vmcnt(12)
	v_pk_add_f32 v[244:245], v[244:245], v[180:181] op_sel_hi:[1,0] neg_lo:[0,1] neg_hi:[0,1]
	v_pk_add_f32 v[246:247], v[246:247], v[180:181] op_sel_hi:[1,0] neg_lo:[0,1] neg_hi:[0,1]
	v_pk_mul_f32 v[244:245], v[244:245], v[180:181] op_sel:[0,1] op_sel_hi:[1,1]
	v_pk_mul_f32 v[246:247], v[246:247], v[180:181] op_sel:[0,1] op_sel_hi:[1,1]
	v_pk_fma_f32 v[244:245], v[244:245], v[154:155], v[162:163]
	v_pk_fma_f32 v[246:247], v[246:247], v[156:157], v[164:165]
	v_pk_fma_f32 v[190:191], v[244:245], s[16:17], v[190:191] op_sel_hi:[1,0,1]
	v_pk_fma_f32 v[192:193], v[246:247], s[16:17], v[192:193] op_sel_hi:[1,0,1]
	global_store_dwordx4 v140, v[190:193], s[88:89]
	ds_write_b128 v144, v[34:37]
	ds_write_b128 v144, v[30:33] offset:1024
	ds_read_b128 v[186:189], v145
	ds_read_b128 v[190:193], v145 offset:512
	s_waitcnt lgkmcnt(4)
	s_waitcnt vmcnt(14)
	v_pk_add_f32 v[204:205], v[204:205], v[178:179] op_sel_hi:[1,0] neg_lo:[0,1] neg_hi:[0,1]
	v_pk_add_f32 v[206:207], v[206:207], v[178:179] op_sel_hi:[1,0] neg_lo:[0,1] neg_hi:[0,1]
	v_pk_mul_f32 v[204:205], v[204:205], v[178:179] op_sel:[0,1] op_sel_hi:[1,1]
	v_pk_mul_f32 v[206:207], v[206:207], v[178:179] op_sel:[0,1] op_sel_hi:[1,1]
	v_pk_fma_f32 v[204:205], v[204:205], v[166:167], v[170:171]
	v_pk_fma_f32 v[206:207], v[206:207], v[168:169], v[172:173]
	v_pk_fma_f32 v[194:195], v[204:205], s[16:17], v[194:195] op_sel_hi:[1,0,1]
	v_pk_fma_f32 v[196:197], v[206:207], s[16:17], v[196:197] op_sel_hi:[1,0,1]
	global_store_dwordx4 v140, v[194:197], s[66:67] offset:512
	s_waitcnt vmcnt(14)
	v_pk_add_f32 v[208:209], v[208:209], v[180:181] op_sel_hi:[1,0] neg_lo:[0,1] neg_hi:[0,1]
	v_pk_add_f32 v[210:211], v[210:211], v[180:181] op_sel_hi:[1,0] neg_lo:[0,1] neg_hi:[0,1]
	v_pk_mul_f32 v[208:209], v[208:209], v[180:181] op_sel:[0,1] op_sel_hi:[1,1]
	v_pk_mul_f32 v[210:211], v[210:211], v[180:181] op_sel:[0,1] op_sel_hi:[1,1]
	v_pk_fma_f32 v[208:209], v[208:209], v[166:167], v[170:171]
	v_pk_fma_f32 v[210:211], v[210:211], v[168:169], v[172:173]
	v_pk_fma_f32 v[198:199], v[208:209], s[16:17], v[198:199] op_sel_hi:[1,0,1]
	v_pk_fma_f32 v[200:201], v[210:211], s[16:17], v[200:201] op_sel_hi:[1,0,1]
	global_store_dwordx4 v140, v[198:201], s[88:89] offset:512
	global_load_dwordx2 v[178:179], v141, s[76:77] offset:1408
	global_load_dwordx2 v[180:181], v141, s[76:77] offset:1472
	ds_write_b128 v144, v[26:29]
	ds_write_b128 v144, v[22:25] offset:1024
	ds_read_b128 v[194:197], v145
	ds_read_b128 v[198:201], v145 offset:512
	s_waitcnt lgkmcnt(4)
	s_waitcnt vmcnt(8)
	v_pk_add_f32 v[212:213], v[212:213], v[174:175] op_sel_hi:[1,0] neg_lo:[0,1] neg_hi:[0,1]
	v_pk_add_f32 v[214:215], v[214:215], v[174:175] op_sel_hi:[1,0] neg_lo:[0,1] neg_hi:[0,1]
	v_pk_mul_f32 v[212:213], v[212:213], v[174:175] op_sel:[0,1] op_sel_hi:[1,1]
	v_pk_mul_f32 v[214:215], v[214:215], v[174:175] op_sel:[0,1] op_sel_hi:[1,1]
	v_pk_fma_f32 v[212:213], v[212:213], v[154:155], v[162:163]
	v_pk_fma_f32 v[214:215], v[214:215], v[156:157], v[164:165]
	v_pk_fma_f32 v[186:187], v[212:213], s[16:17], v[186:187] op_sel_hi:[1,0,1]
	v_pk_fma_f32 v[188:189], v[214:215], s[16:17], v[188:189] op_sel_hi:[1,0,1]
	global_store_dwordx4 v140, v[186:189], s[68:69]
	s_waitcnt vmcnt(8)
	v_pk_add_f32 v[216:217], v[216:217], v[176:177] op_sel_hi:[1,0] neg_lo:[0,1] neg_hi:[0,1]
	v_pk_add_f32 v[218:219], v[218:219], v[176:177] op_sel_hi:[1,0] neg_lo:[0,1] neg_hi:[0,1]
	v_pk_mul_f32 v[216:217], v[216:217], v[176:177] op_sel:[0,1] op_sel_hi:[1,1]
	v_pk_mul_f32 v[218:219], v[218:219], v[176:177] op_sel:[0,1] op_sel_hi:[1,1]
	v_pk_fma_f32 v[216:217], v[216:217], v[154:155], v[162:163]
	v_pk_fma_f32 v[218:219], v[218:219], v[156:157], v[164:165]
	v_pk_fma_f32 v[190:191], v[216:217], s[16:17], v[190:191] op_sel_hi:[1,0,1]
	v_pk_fma_f32 v[192:193], v[218:219], s[16:17], v[192:193] op_sel_hi:[1,0,1]
	global_store_dwordx4 v140, v[190:193], s[90:91]
	ds_write_b128 v144, v[12:15]
	ds_write_b128 v144, v[8:11] offset:1024
	ds_read_b128 v[186:189], v145
	ds_read_b128 v[190:193], v145 offset:512
	s_waitcnt lgkmcnt(4)
; DI void ln_row_wave(const float* src, const float* g, const float* b, float* d32, bf16_t* db, int lane) {
;     ...
;     o.x = (v[i].x - mu) * rstd * gg.x + bb.x; o.y = (v[i].y - mu) * rstd * gg.y + bb.y;
;   DI void operator()(const f32x4 (&acc)[2][2][4][2], const pg8::Unit& u, int wr, int wc, int fr, int fq) const {
;     ...
;               f32x4 x = *reinterpret_cast<const f32x4*>(p.out + idx);
;               x = x * ALPHA + a;
;               *reinterpret_cast<f32x4*>(p.out + idx) = x;
	s_waitcnt vmcnt(10)
	v_pk_add_f32 v[220:221], v[220:221], v[174:175] op_sel_hi:[1,0] neg_lo:[0,1] neg_hi:[0,1]
	v_pk_add_f32 v[222:223], v[222:223], v[174:175] op_sel_hi:[1,0] neg_lo:[0,1] neg_hi:[0,1]
	v_pk_mul_f32 v[220:221], v[220:221], v[174:175] op_sel:[0,1] op_sel_hi:[1,1]
	v_pk_mul_f32 v[222:223], v[222:223], v[174:175] op_sel:[0,1] op_sel_hi:[1,1]
	v_pk_fma_f32 v[220:221], v[220:221], v[166:167], v[170:171]
	v_pk_fma_f32 v[222:223], v[222:223], v[168:169], v[172:173]
	v_pk_fma_f32 v[194:195], v[220:221], s[16:17], v[194:195] op_sel_hi:[1,0,1]
	v_pk_fma_f32 v[196:197], v[222:223], s[16:17], v[196:197] op_sel_hi:[1,0,1]
	global_store_dwordx4 v140, v[194:197], s[68:69] offset:512
	s_waitcnt vmcnt(10)
	v_pk_add_f32 v[224:225], v[224:225], v[176:177] op_sel_hi:[1,0] neg_lo:[0,1] neg_hi:[0,1]
	v_pk_add_f32 v[226:227], v[226:227], v[176:177] op_sel_hi:[1,0] neg_lo:[0,1] neg_hi:[0,1]
	v_pk_mul_f32 v[224:225], v[224:225], v[176:177] op_sel:[0,1] op_sel_hi:[1,1]
	v_pk_mul_f32 v[226:227], v[226:227], v[176:177] op_sel:[0,1] op_sel_hi:[1,1]
	v_pk_fma_f32 v[224:225], v[224:225], v[166:167], v[170:171]
	v_pk_fma_f32 v[226:227], v[226:227], v[168:169], v[172:173]
	v_pk_fma_f32 v[198:199], v[224:225], s[16:17], v[198:199] op_sel_hi:[1,0,1]
	v_pk_fma_f32 v[200:201], v[226:227], s[16:17], v[200:201] op_sel_hi:[1,0,1]
	global_store_dwordx4 v140, v[198:201], s[90:91] offset:512
	ds_write_b128 v144, v[4:7]
	ds_write_b128 v144, v[0:3] offset:1024
	ds_read_b128 v[194:197], v145
	ds_read_b128 v[198:201], v145 offset:512
	s_waitcnt lgkmcnt(4)
	s_waitcnt vmcnt(5)
	v_pk_add_f32 v[228:229], v[228:229], v[178:179] op_sel_hi:[1,0] neg_lo:[0,1] neg_hi:[0,1]
	v_pk_add_f32 v[230:231], v[230:231], v[178:179] op_sel_hi:[1,0] neg_lo:[0,1] neg_hi:[0,1]
	v_pk_mul_f32 v[228:229], v[228:229], v[178:179] op_sel:[0,1] op_sel_hi:[1,1]
	v_pk_mul_f32 v[230:231], v[230:231], v[178:179] op_sel:[0,1] op_sel_hi:[1,1]
	v_pk_fma_f32 v[228:229], v[228:229], v[154:155], v[162:163]
	v_pk_fma_f32 v[230:231], v[230:231], v[156:157], v[164:165]
	v_pk_fma_f32 v[186:187], v[228:229], s[16:17], v[186:187] op_sel_hi:[1,0,1]
	v_pk_fma_f32 v[188:189], v[230:231], s[16:17], v[188:189] op_sel_hi:[1,0,1]
	global_store_dwordx4 v140, v[186:189], s[70:71]
	s_waitcnt vmcnt(5)
	v_pk_add_f32 v[232:233], v[232:233], v[180:181] op_sel_hi:[1,0] neg_lo:[0,1] neg_hi:[0,1]
	v_pk_add_f32 v[234:235], v[234:235], v[180:181] op_sel_hi:[1,0] neg_lo:[0,1] neg_hi:[0,1]
	v_pk_mul_f32 v[232:233], v[232:233], v[180:181] op_sel:[0,1] op_sel_hi:[1,1]
	v_pk_mul_f32 v[234:235], v[234:235], v[180:181] op_sel:[0,1] op_sel_hi:[1,1]
	v_pk_fma_f32 v[232:233], v[232:233], v[154:155], v[162:163]
	v_pk_fma_f32 v[234:235], v[234:235], v[156:157], v[164:165]
	v_pk_fma_f32 v[190:191], v[232:233], s[16:17], v[190:191] op_sel_hi:[1,0,1]
	v_pk_fma_f32 v[192:193], v[234:235], s[16:17], v[192:193] op_sel_hi:[1,0,1]
	global_store_dwordx4 v140, v[190:193], s[92:93]
	s_waitcnt lgkmcnt(0)
	s_waitcnt vmcnt(7)
	v_pk_add_f32 v[236:237], v[236:237], v[178:179] op_sel_hi:[1,0] neg_lo:[0,1] neg_hi:[0,1]
	v_pk_add_f32 v[238:239], v[238:239], v[178:179] op_sel_hi:[1,0] neg_lo:[0,1] neg_hi:[0,1]
	v_pk_mul_f32 v[236:237], v[236:237], v[178:179] op_sel:[0,1] op_sel_hi:[1,1]
	v_pk_mul_f32 v[238:239], v[238:239], v[178:179] op_sel:[0,1] op_sel_hi:[1,1]
	v_pk_fma_f32 v[236:237], v[236:237], v[166:167], v[170:171]
	v_pk_fma_f32 v[238:239], v[238:239], v[168:169], v[172:173]
	v_pk_fma_f32 v[194:195], v[236:237], s[16:17], v[194:195] op_sel_hi:[1,0,1]
	v_pk_fma_f32 v[196:197], v[238:239], s[16:17], v[196:197] op_sel_hi:[1,0,1]
	global_store_dwordx4 v140, v[194:197], s[70:71] offset:512
	s_waitcnt vmcnt(7)
	v_pk_add_f32 v[240:241], v[240:241], v[180:181] op_sel_hi:[1,0] neg_lo:[0,1] neg_hi:[0,1]
	v_pk_add_f32 v[242:243], v[242:243], v[180:181] op_sel_hi:[1,0] neg_lo:[0,1] neg_hi:[0,1]
	v_pk_mul_f32 v[240:241], v[240:241], v[180:181] op_sel:[0,1] op_sel_hi:[1,1]
	v_pk_mul_f32 v[242:243], v[242:243], v[180:181] op_sel:[0,1] op_sel_hi:[1,1]
	v_pk_fma_f32 v[240:241], v[240:241], v[166:167], v[170:171]
	v_pk_fma_f32 v[242:243], v[242:243], v[168:169], v[172:173]
	v_pk_fma_f32 v[198:199], v[240:241], s[16:17], v[198:199] op_sel_hi:[1,0,1]
	v_pk_fma_f32 v[200:201], v[242:243], s[16:17], v[200:201] op_sel_hi:[1,0,1]
	global_store_dwordx4 v140, v[198:201], s[92:93] offset:512
	s_branch .Llz_join

; DI int otid() { int t = threadIdx.x; asm volatile("" : "+v"(t)); return t; }
; #define PG8_WAIT_V(n) asm volatile("s_waitcnt vmcnt(" #n ")" ::: "memory")
; #define PG8_BAR __builtin_amdgcn_s_barrier()
; DI void gbar(unsigned* ctr, unsigned target) {
;   asm volatile("s_waitcnt vmcnt(0)" ::: "memory");
;   __syncthreads();
;   if (otid() == 0) {
;     __builtin_amdgcn_fence(__ATOMIC_RELEASE, "agent");
;     asm volatile("s_waitcnt vmcnt(0)" ::: "memory");
;     __hip_atomic_fetch_add(ctr, 1u, __ATOMIC_RELAXED, __HIP_MEMORY_SCOPE_AGENT);
;     while (__hip_atomic_load(ctr, __ATOMIC_RELAXED, __HIP_MEMORY_SCOPE_AGENT) < target) __builtin_amdgcn_s_sleep(2);
; template <class Epi, class Sched>
; __device__ __forceinline__ void gemm_phase(PG8_LAS unsigned char* lds, const Gemm g, const Sched& S, const Epi& E) {
;     ...
;     PG8_WAIT_V(0);
;     if (wr == 0) PG8_BAR;
;     PG8_BAR;
.LBB0_2759:
	s_setprio 0
	s_waitcnt vmcnt(0)
	v_readlane_b32 s2, v255, 63
	v_readlane_b32 s3, v249, 7
	s_cmp_lg_u32 s2, 0
	s_cbranch_scc1 .Ltr_o_done
	s_sub_u32 s3, s3, 8
	s_cmp_lt_u32 s3, 8
	s_cbranch_scc0 .Ltr_o_done
	s_waitcnt lgkmcnt(0)
	v_cmp_eq_u32_e32 vcc, 0, v153
	s_and_saveexec_b64 s[0:1], vcc
	s_cbranch_execz .Ltr_o_go
	v_readlane_b32 s4, v249, 44
	v_readlane_b32 s5, v249, 45
	v_readlane_b32 s2, v251, 8
	s_lshl_b32 s2, s2, 3
	s_add_i32 s2, s2, 8
	s_nop 3
	global_load_dword v0, v17, s[4:5] offset:4 sc1
	s_waitcnt vmcnt(0)
	v_cmp_le_u32_e32 vcc, s2, v0
	s_cbranch_vccnz .Ltr_o_spun
